# staggered small/big GEMM order plus rebalanced LDS-DMA staging (4 per load segment) in nine K-loops
# speedup vs baseline: 1.0015x; 1.0015x over previous
.LBB0_397:
	s_add_u32 s100, s40, 0xfff80000
	s_addc_u32 s101, s41, -1
	v_lshl_add_u64 v[220:221], s[100:101], 0, v[130:131]
	v_lshl_add_u64 v[222:223], s[100:101], 0, v[134:135]
	ds_read_b128 v[146:149], v155
	ds_read_b128 v[158:161], v155 offset:1024
	ds_read_b128 v[162:165], v155 offset:2048
	ds_read_b128 v[166:169], v155 offset:3072
	ds_read_b128 v[170:173], v156
	ds_read_b128 v[174:177], v156 offset:1024
	ds_read_b128 v[178:181], v156 offset:2048
	ds_read_b128 v[182:185], v156 offset:3072
	s_add_u32 s42, s40, 0xfff80080
	s_addc_u32 s43, s41, -1
	s_cmp_eq_u32 s62, 28
	s_cselect_b32 s45, s31, s43
	s_cselect_b32 s44, s58, s42
	s_cselect_b32 s43, s29, s61
	s_cselect_b32 s42, s59, s60
	v_lshl_add_u64 v[150:151], s[40:41], 0, v[140:141]
	ds_read_b128 v[186:189], v157
	ds_read_b128 v[190:193], v157 offset:1024
	ds_read_b128 v[194:197], v157 offset:2048
	ds_read_b128 v[198:201], v157 offset:3072
	ds_read_b128 v[202:205], v157 offset:4096
	ds_read_b128 v[206:209], v157 offset:5120
	ds_read_b128 v[210:213], v157 offset:6144
	ds_read_b128 v[214:217], v157 offset:7168
	s_mov_b32 m0, s49
	s_nop 0
	global_load_lds_dwordx4 v[220:221], off
	s_mov_b32 m0, s51
	s_nop 0
	global_load_lds_dwordx4 v[222:223], off
	s_add_i32 m0, s33, 0xc000
	s_nop 0
	global_load_lds_dwordx4 v[150:151], off
	v_lshl_add_u64 v[150:151], s[40:41], 0, v[138:139]
	s_add_i32 m0, s33, 0xe000
	s_nop 0
	global_load_lds_dwordx4 v[150:151], off
	s_waitcnt vmcnt(8)
	s_waitcnt lgkmcnt(0)
	s_barrier
	s_setprio 1
	s_waitcnt lgkmcnt(0)
	v_mfma_f32_16x16x32_bf16 v[126:129], v[146:149], v[186:189], v[126:129]
	v_mfma_f32_16x16x32_bf16 v[122:125], v[162:165], v[186:189], v[122:125]
	v_mfma_f32_16x16x32_bf16 v[110:113], v[146:149], v[194:197], v[110:113]
	v_mfma_f32_16x16x32_bf16 v[106:109], v[162:165], v[194:197], v[106:109]
	v_mfma_f32_16x16x32_bf16 v[94:97], v[146:149], v[202:205], v[94:97]
	v_mfma_f32_16x16x32_bf16 v[90:93], v[162:165], v[202:205], v[90:93]
	v_mfma_f32_16x16x32_bf16 v[78:81], v[146:149], v[210:213], v[78:81]
	v_mfma_f32_16x16x32_bf16 v[74:77], v[162:165], v[210:213], v[74:77]
	v_mfma_f32_16x16x32_bf16 v[126:129], v[158:161], v[190:193], v[126:129]
	v_mfma_f32_16x16x32_bf16 v[122:125], v[166:169], v[190:193], v[122:125]
	v_mfma_f32_16x16x32_bf16 v[110:113], v[158:161], v[198:201], v[110:113]
	v_mfma_f32_16x16x32_bf16 v[106:109], v[166:169], v[198:201], v[106:109]
	v_mfma_f32_16x16x32_bf16 v[94:97], v[158:161], v[206:209], v[94:97]
	v_mfma_f32_16x16x32_bf16 v[90:93], v[166:169], v[206:209], v[90:93]
	v_mfma_f32_16x16x32_bf16 v[78:81], v[158:161], v[214:217], v[78:81]
	v_mfma_f32_16x16x32_bf16 v[74:77], v[166:169], v[214:217], v[74:77]
	s_setprio 0
	s_setprio 1
	v_mfma_f32_16x16x32_bf16 v[118:121], v[170:173], v[186:189], v[118:121]
	v_mfma_f32_16x16x32_bf16 v[114:117], v[178:181], v[186:189], v[114:117]
	v_mfma_f32_16x16x32_bf16 v[102:105], v[170:173], v[194:197], v[102:105]
	v_mfma_f32_16x16x32_bf16 v[98:101], v[178:181], v[194:197], v[98:101]
	v_mfma_f32_16x16x32_bf16 v[86:89], v[170:173], v[202:205], v[86:89]
	v_mfma_f32_16x16x32_bf16 v[82:85], v[178:181], v[202:205], v[82:85]
	v_mfma_f32_16x16x32_bf16 v[70:73], v[170:173], v[210:213], v[70:73]
	v_mfma_f32_16x16x32_bf16 v[66:69], v[178:181], v[210:213], v[66:69]
	v_mfma_f32_16x16x32_bf16 v[118:121], v[174:177], v[190:193], v[118:121]
	v_mfma_f32_16x16x32_bf16 v[114:117], v[182:185], v[190:193], v[114:117]
	v_mfma_f32_16x16x32_bf16 v[102:105], v[174:177], v[198:201], v[102:105]
	v_mfma_f32_16x16x32_bf16 v[98:101], v[182:185], v[198:201], v[98:101]
	v_mfma_f32_16x16x32_bf16 v[86:89], v[174:177], v[206:209], v[86:89]
	v_mfma_f32_16x16x32_bf16 v[82:85], v[182:185], v[206:209], v[82:85]
	v_mfma_f32_16x16x32_bf16 v[70:73], v[174:177], v[214:217], v[70:73]
	v_mfma_f32_16x16x32_bf16 v[66:69], v[182:185], v[214:217], v[66:69]
	s_setprio 0
	s_barrier
	s_add_i32 s63, s53, s1
	v_lshl_add_u64 v[150:151], s[42:43], 0, v[132:133]
	s_mov_b32 m0, s63
	ds_read_b128 v[186:189], v157 offset:16384
	ds_read_b128 v[190:193], v157 offset:17408
	ds_read_b128 v[194:197], v157 offset:18432
	ds_read_b128 v[198:201], v157 offset:19456
	ds_read_b128 v[202:205], v157 offset:20480
	ds_read_b128 v[206:209], v157 offset:21504
	ds_read_b128 v[210:213], v157 offset:22528
	ds_read_b128 v[214:217], v157 offset:23552
	global_load_lds_dwordx4 v[150:151], off
	s_add_i32 m0, s63, 0x2000
	s_add_u32 s64, s42, 0x80000
	v_lshl_add_u64 v[218:219], s[42:43], 0, v[136:137]
	s_addc_u32 s65, s43, 0
	s_add_i32 s63, s56, s1
	global_load_lds_dwordx4 v[218:219], off
	v_lshl_add_u64 v[220:221], s[64:65], 0, v[132:133]
	s_mov_b32 m0, s63
	v_lshl_add_u64 v[222:223], s[44:45], 0, v[134:135]
	global_load_lds_dwordx4 v[220:221], off
	v_lshl_add_u64 v[220:221], s[64:65], 0, v[136:137]
	s_add_i32 m0, s63, 0x2000
	s_nop 0
	global_load_lds_dwordx4 v[220:221], off
	v_lshl_add_u64 v[220:221], s[44:45], 0, v[130:131]
	s_waitcnt vmcnt(6)
	s_waitcnt lgkmcnt(0)
	s_barrier
	s_setprio 1
	s_waitcnt lgkmcnt(0)
	v_mfma_f32_16x16x32_bf16 v[62:65], v[146:149], v[186:189], v[62:65]
	v_mfma_f32_16x16x32_bf16 v[58:61], v[162:165], v[186:189], v[58:61]
	v_mfma_f32_16x16x32_bf16 v[46:49], v[146:149], v[194:197], v[46:49]
	v_mfma_f32_16x16x32_bf16 v[42:45], v[162:165], v[194:197], v[42:45]
	v_mfma_f32_16x16x32_bf16 v[30:33], v[146:149], v[202:205], v[30:33]
	v_mfma_f32_16x16x32_bf16 v[26:29], v[162:165], v[202:205], v[26:29]
	v_mfma_f32_16x16x32_bf16 v[14:17], v[146:149], v[210:213], v[14:17]
	v_mfma_f32_16x16x32_bf16 v[10:13], v[162:165], v[210:213], v[10:13]
	v_mfma_f32_16x16x32_bf16 v[62:65], v[158:161], v[190:193], v[62:65]
	v_mfma_f32_16x16x32_bf16 v[58:61], v[166:169], v[190:193], v[58:61]
	v_mfma_f32_16x16x32_bf16 v[46:49], v[158:161], v[198:201], v[46:49]
	v_mfma_f32_16x16x32_bf16 v[42:45], v[166:169], v[198:201], v[42:45]
	v_mfma_f32_16x16x32_bf16 v[30:33], v[158:161], v[206:209], v[30:33]
	v_mfma_f32_16x16x32_bf16 v[26:29], v[166:169], v[206:209], v[26:29]
	v_mfma_f32_16x16x32_bf16 v[14:17], v[158:161], v[214:217], v[14:17]
	v_mfma_f32_16x16x32_bf16 v[10:13], v[166:169], v[214:217], v[10:13]
	s_setprio 0
	s_setprio 1
	v_mfma_f32_16x16x32_bf16 v[54:57], v[170:173], v[186:189], v[54:57]
	v_mfma_f32_16x16x32_bf16 v[50:53], v[178:181], v[186:189], v[50:53]
	v_mfma_f32_16x16x32_bf16 v[38:41], v[170:173], v[194:197], v[38:41]
	v_mfma_f32_16x16x32_bf16 v[34:37], v[178:181], v[194:197], v[34:37]
	v_mfma_f32_16x16x32_bf16 v[22:25], v[170:173], v[202:205], v[22:25]
	v_mfma_f32_16x16x32_bf16 v[18:21], v[178:181], v[202:205], v[18:21]
	v_mfma_f32_16x16x32_bf16 v[6:9], v[170:173], v[210:213], v[6:9]
	v_mfma_f32_16x16x32_bf16 v[2:5], v[178:181], v[210:213], v[2:5]
	v_mfma_f32_16x16x32_bf16 v[54:57], v[174:177], v[190:193], v[54:57]
	v_mfma_f32_16x16x32_bf16 v[50:53], v[182:185], v[190:193], v[50:53]
	v_mfma_f32_16x16x32_bf16 v[38:41], v[174:177], v[198:201], v[38:41]
	v_mfma_f32_16x16x32_bf16 v[34:37], v[182:185], v[198:201], v[34:37]
	v_mfma_f32_16x16x32_bf16 v[22:25], v[174:177], v[206:209], v[22:25]
	v_mfma_f32_16x16x32_bf16 v[18:21], v[182:185], v[206:209], v[18:21]
	v_mfma_f32_16x16x32_bf16 v[6:9], v[174:177], v[214:217], v[6:9]
	v_mfma_f32_16x16x32_bf16 v[2:5], v[182:185], v[214:217], v[2:5]
	s_setprio 0
	s_barrier
	s_add_i32 s63, 0, 0x18000
	s_add_i32 s64, 0, 0x1c000
	v_add_u32_e32 v166, s63, v153
	v_add_u32_e32 v182, s64, v153
	ds_read_b128 v[146:149], v166
	ds_read_b128 v[158:161], v166 offset:1024
	ds_read_b128 v[162:165], v166 offset:2048
	ds_read_b128 v[166:169], v166 offset:3072
	ds_read_b128 v[170:173], v182
	ds_read_b128 v[174:177], v182 offset:1024
	ds_read_b128 v[178:181], v182 offset:2048
	ds_read_b128 v[182:185], v182 offset:3072
	s_add_u32 s44, s44, 0x80000
	s_addc_u32 s45, s45, 0
	v_lshl_add_u64 v[224:225], s[44:45], 0, v[130:131]
	ds_read_b128 v[186:189], v157 offset:32768
	ds_read_b128 v[190:193], v157 offset:33792
	ds_read_b128 v[194:197], v157 offset:34816
	ds_read_b128 v[198:201], v157 offset:35840
	ds_read_b128 v[202:205], v157 offset:36864
	ds_read_b128 v[206:209], v157 offset:37888
	ds_read_b128 v[210:213], v157 offset:38912
	ds_read_b128 v[214:217], v157 offset:39936
	s_mov_b32 m0, s33
	s_nop 0
	global_load_lds_dwordx4 v[220:221], off
	s_mov_b32 m0, s39
	s_nop 0
	global_load_lds_dwordx4 v[222:223], off
	s_mov_b32 m0, s46
	s_nop 0
	global_load_lds_dwordx4 v[224:225], off
	v_lshl_add_u64 v[224:225], s[44:45], 0, v[134:135]
	s_mov_b32 m0, s47
	s_nop 0
	global_load_lds_dwordx4 v[224:225], off
	s_waitcnt vmcnt(8)
	s_waitcnt lgkmcnt(0)
	s_barrier
	s_setprio 1
	s_waitcnt lgkmcnt(0)
	v_mfma_f32_16x16x32_bf16 v[126:129], v[146:149], v[186:189], v[126:129]
	v_mfma_f32_16x16x32_bf16 v[122:125], v[162:165], v[186:189], v[122:125]
	v_mfma_f32_16x16x32_bf16 v[110:113], v[146:149], v[194:197], v[110:113]
	v_mfma_f32_16x16x32_bf16 v[106:109], v[162:165], v[194:197], v[106:109]
	v_mfma_f32_16x16x32_bf16 v[94:97], v[146:149], v[202:205], v[94:97]
	v_mfma_f32_16x16x32_bf16 v[90:93], v[162:165], v[202:205], v[90:93]
	v_mfma_f32_16x16x32_bf16 v[78:81], v[146:149], v[210:213], v[78:81]
	v_mfma_f32_16x16x32_bf16 v[74:77], v[162:165], v[210:213], v[74:77]
	v_mfma_f32_16x16x32_bf16 v[126:129], v[158:161], v[190:193], v[126:129]
	v_mfma_f32_16x16x32_bf16 v[122:125], v[166:169], v[190:193], v[122:125]
	v_mfma_f32_16x16x32_bf16 v[110:113], v[158:161], v[198:201], v[110:113]
	v_mfma_f32_16x16x32_bf16 v[106:109], v[166:169], v[198:201], v[106:109]
	v_mfma_f32_16x16x32_bf16 v[94:97], v[158:161], v[206:209], v[94:97]
	v_mfma_f32_16x16x32_bf16 v[90:93], v[166:169], v[206:209], v[90:93]
	v_mfma_f32_16x16x32_bf16 v[78:81], v[158:161], v[214:217], v[78:81]
	v_mfma_f32_16x16x32_bf16 v[74:77], v[166:169], v[214:217], v[74:77]
	s_setprio 0
	s_setprio 1
	v_mfma_f32_16x16x32_bf16 v[118:121], v[170:173], v[186:189], v[118:121]
	v_mfma_f32_16x16x32_bf16 v[114:117], v[178:181], v[186:189], v[114:117]
	v_mfma_f32_16x16x32_bf16 v[102:105], v[170:173], v[194:197], v[102:105]
	v_mfma_f32_16x16x32_bf16 v[98:101], v[178:181], v[194:197], v[98:101]
	v_mfma_f32_16x16x32_bf16 v[86:89], v[170:173], v[202:205], v[86:89]
	v_mfma_f32_16x16x32_bf16 v[82:85], v[178:181], v[202:205], v[82:85]
	v_mfma_f32_16x16x32_bf16 v[70:73], v[170:173], v[210:213], v[70:73]
	v_mfma_f32_16x16x32_bf16 v[66:69], v[178:181], v[210:213], v[66:69]
	v_mfma_f32_16x16x32_bf16 v[118:121], v[174:177], v[190:193], v[118:121]
	v_mfma_f32_16x16x32_bf16 v[114:117], v[182:185], v[190:193], v[114:117]
	v_mfma_f32_16x16x32_bf16 v[102:105], v[174:177], v[198:201], v[102:105]
	v_mfma_f32_16x16x32_bf16 v[98:101], v[182:185], v[198:201], v[98:101]
	v_mfma_f32_16x16x32_bf16 v[86:89], v[174:177], v[206:209], v[86:89]
	v_mfma_f32_16x16x32_bf16 v[82:85], v[182:185], v[206:209], v[82:85]
	v_mfma_f32_16x16x32_bf16 v[70:73], v[174:177], v[214:217], v[70:73]
	v_mfma_f32_16x16x32_bf16 v[66:69], v[182:185], v[214:217], v[66:69]
	s_setprio 0
	s_barrier
	s_add_i32 s44, s63, s1
	v_lshl_add_u64 v[150:151], v[150:151], 0, s[18:19]
	s_mov_b32 m0, s44
	ds_read_b128 v[186:189], v157 offset:49152
	ds_read_b128 v[190:193], v157 offset:50176
	ds_read_b128 v[194:197], v157 offset:51200
	ds_read_b128 v[198:201], v157 offset:52224
	ds_read_b128 v[202:205], v157 offset:53248
	ds_read_b128 v[206:209], v157 offset:54272
	ds_read_b128 v[210:213], v157 offset:55296
	ds_read_b128 v[214:217], v157 offset:56320
	global_load_lds_dwordx4 v[150:151], off
	s_add_i32 m0, s44, 0x2000
	s_add_u32 s42, s42, 0x80080
	v_lshl_add_u64 v[150:151], v[218:219], 0, s[18:19]
	s_addc_u32 s43, s43, 0
	s_add_i32 s44, s64, s1
	global_load_lds_dwordx4 v[150:151], off
	v_lshl_add_u64 v[150:151], s[42:43], 0, v[132:133]
	s_mov_b32 m0, s44
	s_nop 0
	global_load_lds_dwordx4 v[150:151], off
	v_lshl_add_u64 v[150:151], s[42:43], 0, v[136:137]
	s_add_i32 m0, s44, 0x2000
	s_nop 0
	global_load_lds_dwordx4 v[150:151], off
	s_waitcnt vmcnt(6)
	s_waitcnt lgkmcnt(0)
	s_barrier
	s_setprio 1
	s_waitcnt lgkmcnt(0)
	v_mfma_f32_16x16x32_bf16 v[62:65], v[146:149], v[186:189], v[62:65]
	v_mfma_f32_16x16x32_bf16 v[58:61], v[162:165], v[186:189], v[58:61]
	v_mfma_f32_16x16x32_bf16 v[46:49], v[146:149], v[194:197], v[46:49]
	v_mfma_f32_16x16x32_bf16 v[42:45], v[162:165], v[194:197], v[42:45]
	v_mfma_f32_16x16x32_bf16 v[30:33], v[146:149], v[202:205], v[30:33]
	v_mfma_f32_16x16x32_bf16 v[26:29], v[162:165], v[202:205], v[26:29]
	v_mfma_f32_16x16x32_bf16 v[14:17], v[146:149], v[210:213], v[14:17]
	v_mfma_f32_16x16x32_bf16 v[10:13], v[162:165], v[210:213], v[10:13]
	v_mfma_f32_16x16x32_bf16 v[62:65], v[158:161], v[190:193], v[62:65]
	v_mfma_f32_16x16x32_bf16 v[58:61], v[166:169], v[190:193], v[58:61]
	v_mfma_f32_16x16x32_bf16 v[46:49], v[158:161], v[198:201], v[46:49]
	v_mfma_f32_16x16x32_bf16 v[42:45], v[166:169], v[198:201], v[42:45]
	v_mfma_f32_16x16x32_bf16 v[30:33], v[158:161], v[206:209], v[30:33]
	v_mfma_f32_16x16x32_bf16 v[26:29], v[166:169], v[206:209], v[26:29]
	v_mfma_f32_16x16x32_bf16 v[14:17], v[158:161], v[214:217], v[14:17]
	v_mfma_f32_16x16x32_bf16 v[10:13], v[166:169], v[214:217], v[10:13]
	s_setprio 0
	s_setprio 1
	v_mfma_f32_16x16x32_bf16 v[54:57], v[170:173], v[186:189], v[54:57]
	v_mfma_f32_16x16x32_bf16 v[50:53], v[178:181], v[186:189], v[50:53]
	v_mfma_f32_16x16x32_bf16 v[38:41], v[170:173], v[194:197], v[38:41]
	v_mfma_f32_16x16x32_bf16 v[34:37], v[178:181], v[194:197], v[34:37]
	v_mfma_f32_16x16x32_bf16 v[22:25], v[170:173], v[202:205], v[22:25]
	v_mfma_f32_16x16x32_bf16 v[18:21], v[178:181], v[202:205], v[18:21]
	v_mfma_f32_16x16x32_bf16 v[6:9], v[170:173], v[210:213], v[6:9]
	v_mfma_f32_16x16x32_bf16 v[2:5], v[178:181], v[210:213], v[2:5]
	v_mfma_f32_16x16x32_bf16 v[54:57], v[174:177], v[190:193], v[54:57]
	v_mfma_f32_16x16x32_bf16 v[50:53], v[182:185], v[190:193], v[50:53]
	v_mfma_f32_16x16x32_bf16 v[38:41], v[174:177], v[198:201], v[38:41]
	v_mfma_f32_16x16x32_bf16 v[34:37], v[182:185], v[198:201], v[34:37]
	v_mfma_f32_16x16x32_bf16 v[22:25], v[174:177], v[206:209], v[22:25]
	v_mfma_f32_16x16x32_bf16 v[18:21], v[182:185], v[206:209], v[18:21]
	v_mfma_f32_16x16x32_bf16 v[6:9], v[174:177], v[214:217], v[6:9]
	v_mfma_f32_16x16x32_bf16 v[2:5], v[182:185], v[214:217], v[2:5]
	s_setprio 0
	s_barrier
	s_add_i32 s62, s62, 2
	s_add_u32 s60, s60, 0x100
	s_addc_u32 s61, s61, 0
	s_add_u32 s40, s40, 0x100
	s_addc_u32 s41, s41, 0
	s_cmp_gt_u32 s62, 29
	s_cbranch_scc0 .LBB0_397
	s_and_b64 vcc, exec, s[20:21]
	s_cbranch_vccz .LBB0_400
	s_barrier

.LBB0_477:
	s_add_u32 s100, s46, 0xfff80000
	s_addc_u32 s101, s47, -1
	v_lshl_add_u64 v[228:229], s[100:101], 0, v[130:131]
	v_lshl_add_u64 v[230:231], s[100:101], 0, v[134:135]
	ds_read_b128 v[148:151], v159
	ds_read_b128 v[164:167], v159 offset:1024
	ds_read_b128 v[168:171], v159 offset:2048
	ds_read_b128 v[172:175], v159 offset:3072
	ds_read_b128 v[176:179], v160
	ds_read_b128 v[180:183], v160 offset:1024
	ds_read_b128 v[184:187], v160 offset:2048
	ds_read_b128 v[188:191], v160 offset:3072
	s_add_u32 s58, s46, 0xfff80080
	s_addc_u32 s59, s47, -1
	s_cmp_eq_u32 s65, 28
	s_cselect_b32 s61, s37, s59
	s_cselect_b32 s60, s43, s58
	s_cselect_b32 s59, s35, s64
	s_cselect_b32 s58, s62, s63
	v_lshl_add_u64 v[220:221], s[46:47], 0, v[142:143]
	ds_read_b128 v[192:195], v161
	ds_read_b128 v[196:199], v161 offset:1024
	ds_read_b128 v[200:203], v161 offset:2048
	ds_read_b128 v[204:207], v161 offset:3072
	ds_read_b128 v[208:211], v161 offset:4096
	ds_read_b128 v[212:215], v161 offset:5120
	ds_read_b128 v[216:219], v161 offset:6144
	ds_read_b128 v[224:227], v161 offset:7168
	s_mov_b32 m0, s49
	s_nop 0
	global_load_lds_dwordx4 v[228:229], off
	s_mov_b32 m0, s51
	s_nop 0
	global_load_lds_dwordx4 v[230:231], off
	s_add_i32 m0, s1, 0xc000
	s_nop 0
	global_load_lds_dwordx4 v[220:221], off
	v_lshl_add_u64 v[220:221], s[46:47], 0, v[140:141]
	s_add_i32 m0, s1, 0xe000
	s_nop 0
	global_load_lds_dwordx4 v[220:221], off
	s_waitcnt vmcnt(8)
	s_waitcnt lgkmcnt(0)
	s_barrier
	s_setprio 1
	s_waitcnt lgkmcnt(0)
	v_mfma_f32_16x16x32_bf16 v[126:129], v[148:151], v[192:195], v[126:129]
	v_mfma_f32_16x16x32_bf16 v[122:125], v[168:171], v[192:195], v[122:125]
	v_mfma_f32_16x16x32_bf16 v[110:113], v[148:151], v[200:203], v[110:113]
	v_mfma_f32_16x16x32_bf16 v[106:109], v[168:171], v[200:203], v[106:109]
	v_mfma_f32_16x16x32_bf16 v[94:97], v[148:151], v[208:211], v[94:97]
	v_mfma_f32_16x16x32_bf16 v[90:93], v[168:171], v[208:211], v[90:93]
	v_mfma_f32_16x16x32_bf16 v[78:81], v[148:151], v[216:219], v[78:81]
	v_mfma_f32_16x16x32_bf16 v[74:77], v[168:171], v[216:219], v[74:77]
	v_mfma_f32_16x16x32_bf16 v[126:129], v[164:167], v[196:199], v[126:129]
	v_mfma_f32_16x16x32_bf16 v[122:125], v[172:175], v[196:199], v[122:125]
	v_mfma_f32_16x16x32_bf16 v[110:113], v[164:167], v[204:207], v[110:113]
	v_mfma_f32_16x16x32_bf16 v[106:109], v[172:175], v[204:207], v[106:109]
	v_mfma_f32_16x16x32_bf16 v[94:97], v[164:167], v[212:215], v[94:97]
	v_mfma_f32_16x16x32_bf16 v[90:93], v[172:175], v[212:215], v[90:93]
	v_mfma_f32_16x16x32_bf16 v[78:81], v[164:167], v[224:227], v[78:81]
	v_mfma_f32_16x16x32_bf16 v[74:77], v[172:175], v[224:227], v[74:77]
	s_setprio 0
	s_setprio 1
	v_mfma_f32_16x16x32_bf16 v[118:121], v[176:179], v[192:195], v[118:121]
	v_mfma_f32_16x16x32_bf16 v[114:117], v[184:187], v[192:195], v[114:117]
	v_mfma_f32_16x16x32_bf16 v[102:105], v[176:179], v[200:203], v[102:105]
	v_mfma_f32_16x16x32_bf16 v[98:101], v[184:187], v[200:203], v[98:101]
	v_mfma_f32_16x16x32_bf16 v[86:89], v[176:179], v[208:211], v[86:89]
	v_mfma_f32_16x16x32_bf16 v[82:85], v[184:187], v[208:211], v[82:85]
	v_mfma_f32_16x16x32_bf16 v[70:73], v[176:179], v[216:219], v[70:73]
	v_mfma_f32_16x16x32_bf16 v[66:69], v[184:187], v[216:219], v[66:69]
	v_mfma_f32_16x16x32_bf16 v[118:121], v[180:183], v[196:199], v[118:121]
	v_mfma_f32_16x16x32_bf16 v[114:117], v[188:191], v[196:199], v[114:117]
	v_mfma_f32_16x16x32_bf16 v[102:105], v[180:183], v[204:207], v[102:105]
	v_mfma_f32_16x16x32_bf16 v[98:101], v[188:191], v[204:207], v[98:101]
	v_mfma_f32_16x16x32_bf16 v[86:89], v[180:183], v[212:215], v[86:89]
	v_mfma_f32_16x16x32_bf16 v[82:85], v[188:191], v[212:215], v[82:85]
	v_mfma_f32_16x16x32_bf16 v[70:73], v[180:183], v[224:227], v[70:73]
	v_mfma_f32_16x16x32_bf16 v[66:69], v[188:191], v[224:227], v[66:69]
	s_setprio 0
	s_barrier
	s_add_i32 s66, s56, s0
	v_lshl_add_u64 v[220:221], s[58:59], 0, v[132:133]
	s_mov_b32 m0, s66
	ds_read_b128 v[192:195], v161 offset:16384
	ds_read_b128 v[196:199], v161 offset:17408
	ds_read_b128 v[200:203], v161 offset:18432
	ds_read_b128 v[204:207], v161 offset:19456
	ds_read_b128 v[208:211], v161 offset:20480
	ds_read_b128 v[212:215], v161 offset:21504
	ds_read_b128 v[216:219], v161 offset:22528
	ds_read_b128 v[224:227], v161 offset:23552
	global_load_lds_dwordx4 v[220:221], off
	s_add_i32 m0, s66, 0x2000
	s_add_u32 s66, s58, 0x80000
	v_lshl_add_u64 v[222:223], s[58:59], 0, v[136:137]
	s_addc_u32 s67, s59, 0
	s_add_i32 s68, s57, s0
	global_load_lds_dwordx4 v[222:223], off
	v_lshl_add_u64 v[228:229], s[66:67], 0, v[132:133]
	s_mov_b32 m0, s68
	v_lshl_add_u64 v[230:231], s[60:61], 0, v[134:135]
	global_load_lds_dwordx4 v[228:229], off
	v_lshl_add_u64 v[228:229], s[66:67], 0, v[136:137]
	s_add_i32 m0, s68, 0x2000
	s_nop 0
	global_load_lds_dwordx4 v[228:229], off
	v_lshl_add_u64 v[228:229], s[60:61], 0, v[130:131]
	s_waitcnt vmcnt(6)
	s_waitcnt lgkmcnt(0)
	s_barrier
	s_setprio 1
	s_waitcnt lgkmcnt(0)
	v_mfma_f32_16x16x32_bf16 v[62:65], v[148:151], v[192:195], v[62:65]
	v_mfma_f32_16x16x32_bf16 v[58:61], v[168:171], v[192:195], v[58:61]
	v_mfma_f32_16x16x32_bf16 v[46:49], v[148:151], v[200:203], v[46:49]
	v_mfma_f32_16x16x32_bf16 v[42:45], v[168:171], v[200:203], v[42:45]
	v_mfma_f32_16x16x32_bf16 v[30:33], v[148:151], v[208:211], v[30:33]
	v_mfma_f32_16x16x32_bf16 v[26:29], v[168:171], v[208:211], v[26:29]
	v_mfma_f32_16x16x32_bf16 v[14:17], v[148:151], v[216:219], v[14:17]
	v_mfma_f32_16x16x32_bf16 v[10:13], v[168:171], v[216:219], v[10:13]
	v_mfma_f32_16x16x32_bf16 v[62:65], v[164:167], v[196:199], v[62:65]
	v_mfma_f32_16x16x32_bf16 v[58:61], v[172:175], v[196:199], v[58:61]
	v_mfma_f32_16x16x32_bf16 v[46:49], v[164:167], v[204:207], v[46:49]
	v_mfma_f32_16x16x32_bf16 v[42:45], v[172:175], v[204:207], v[42:45]
	v_mfma_f32_16x16x32_bf16 v[30:33], v[164:167], v[212:215], v[30:33]
	v_mfma_f32_16x16x32_bf16 v[26:29], v[172:175], v[212:215], v[26:29]
	v_mfma_f32_16x16x32_bf16 v[14:17], v[164:167], v[224:227], v[14:17]
	v_mfma_f32_16x16x32_bf16 v[10:13], v[172:175], v[224:227], v[10:13]
	s_setprio 0
	s_setprio 1
	v_mfma_f32_16x16x32_bf16 v[54:57], v[176:179], v[192:195], v[54:57]
	v_mfma_f32_16x16x32_bf16 v[50:53], v[184:187], v[192:195], v[50:53]
	v_mfma_f32_16x16x32_bf16 v[38:41], v[176:179], v[200:203], v[38:41]
	v_mfma_f32_16x16x32_bf16 v[34:37], v[184:187], v[200:203], v[34:37]
	v_mfma_f32_16x16x32_bf16 v[22:25], v[176:179], v[208:211], v[22:25]
	v_mfma_f32_16x16x32_bf16 v[18:21], v[184:187], v[208:211], v[18:21]
	v_mfma_f32_16x16x32_bf16 v[6:9], v[176:179], v[216:219], v[6:9]
	v_mfma_f32_16x16x32_bf16 v[2:5], v[184:187], v[216:219], v[2:5]
	v_mfma_f32_16x16x32_bf16 v[54:57], v[180:183], v[196:199], v[54:57]
	v_mfma_f32_16x16x32_bf16 v[50:53], v[188:191], v[196:199], v[50:53]
	v_mfma_f32_16x16x32_bf16 v[38:41], v[180:183], v[204:207], v[38:41]
	v_mfma_f32_16x16x32_bf16 v[34:37], v[188:191], v[204:207], v[34:37]
	v_mfma_f32_16x16x32_bf16 v[22:25], v[180:183], v[212:215], v[22:25]
	v_mfma_f32_16x16x32_bf16 v[18:21], v[188:191], v[212:215], v[18:21]
	v_mfma_f32_16x16x32_bf16 v[6:9], v[180:183], v[224:227], v[6:9]
	v_mfma_f32_16x16x32_bf16 v[2:5], v[188:191], v[224:227], v[2:5]
	s_setprio 0
	s_barrier
	s_add_i32 s66, 0, 0x18000
	v_add_u32_e32 v163, s66, v154
	s_add_i32 s67, 0, 0x1c000
	ds_read_b128 v[148:151], v163
	ds_read_b128 v[164:167], v163 offset:1024
	ds_read_b128 v[168:171], v163 offset:2048
	ds_read_b128 v[172:175], v163 offset:3072
	v_add_u32_e32 v163, s67, v154
	ds_read_b128 v[176:179], v163
	ds_read_b128 v[180:183], v163 offset:1024
	ds_read_b128 v[184:187], v163 offset:2048
	ds_read_b128 v[188:191], v163 offset:3072
	s_add_u32 s60, s60, 0x80000
	s_addc_u32 s61, s61, 0
	v_lshl_add_u64 v[232:233], s[60:61], 0, v[130:131]
	ds_read_b128 v[192:195], v161 offset:32768
	ds_read_b128 v[196:199], v161 offset:33792
	ds_read_b128 v[200:203], v161 offset:34816
	ds_read_b128 v[204:207], v161 offset:35840
	ds_read_b128 v[208:211], v161 offset:36864
	ds_read_b128 v[212:215], v161 offset:37888
	ds_read_b128 v[216:219], v161 offset:38912
	ds_read_b128 v[224:227], v161 offset:39936
	s_mov_b32 m0, s1
	s_nop 0
	global_load_lds_dwordx4 v[228:229], off
	s_mov_b32 m0, s31
	s_nop 0
	global_load_lds_dwordx4 v[230:231], off
	s_mov_b32 m0, s33
	s_nop 0
	global_load_lds_dwordx4 v[232:233], off
	v_lshl_add_u64 v[232:233], s[60:61], 0, v[134:135]
	s_mov_b32 m0, s45
	s_nop 0
	global_load_lds_dwordx4 v[232:233], off
	s_waitcnt vmcnt(8)
	s_waitcnt lgkmcnt(0)
	s_barrier
	s_setprio 1
	s_waitcnt lgkmcnt(0)
	v_mfma_f32_16x16x32_bf16 v[126:129], v[148:151], v[192:195], v[126:129]
	v_mfma_f32_16x16x32_bf16 v[122:125], v[168:171], v[192:195], v[122:125]
	v_mfma_f32_16x16x32_bf16 v[110:113], v[148:151], v[200:203], v[110:113]
	v_mfma_f32_16x16x32_bf16 v[106:109], v[168:171], v[200:203], v[106:109]
	v_mfma_f32_16x16x32_bf16 v[94:97], v[148:151], v[208:211], v[94:97]
	v_mfma_f32_16x16x32_bf16 v[90:93], v[168:171], v[208:211], v[90:93]
	v_mfma_f32_16x16x32_bf16 v[78:81], v[148:151], v[216:219], v[78:81]
	v_mfma_f32_16x16x32_bf16 v[74:77], v[168:171], v[216:219], v[74:77]
	v_mfma_f32_16x16x32_bf16 v[126:129], v[164:167], v[196:199], v[126:129]
	v_mfma_f32_16x16x32_bf16 v[122:125], v[172:175], v[196:199], v[122:125]
	v_mfma_f32_16x16x32_bf16 v[110:113], v[164:167], v[204:207], v[110:113]
	v_mfma_f32_16x16x32_bf16 v[106:109], v[172:175], v[204:207], v[106:109]
	v_mfma_f32_16x16x32_bf16 v[94:97], v[164:167], v[212:215], v[94:97]
	v_mfma_f32_16x16x32_bf16 v[90:93], v[172:175], v[212:215], v[90:93]
	v_mfma_f32_16x16x32_bf16 v[78:81], v[164:167], v[224:227], v[78:81]
	v_mfma_f32_16x16x32_bf16 v[74:77], v[172:175], v[224:227], v[74:77]
	s_setprio 0
	s_setprio 1
	v_mfma_f32_16x16x32_bf16 v[118:121], v[176:179], v[192:195], v[118:121]
	v_mfma_f32_16x16x32_bf16 v[114:117], v[184:187], v[192:195], v[114:117]
	v_mfma_f32_16x16x32_bf16 v[102:105], v[176:179], v[200:203], v[102:105]
	v_mfma_f32_16x16x32_bf16 v[98:101], v[184:187], v[200:203], v[98:101]
	v_mfma_f32_16x16x32_bf16 v[86:89], v[176:179], v[208:211], v[86:89]
	v_mfma_f32_16x16x32_bf16 v[82:85], v[184:187], v[208:211], v[82:85]
	v_mfma_f32_16x16x32_bf16 v[70:73], v[176:179], v[216:219], v[70:73]
	v_mfma_f32_16x16x32_bf16 v[66:69], v[184:187], v[216:219], v[66:69]
	v_mfma_f32_16x16x32_bf16 v[118:121], v[180:183], v[196:199], v[118:121]
	v_mfma_f32_16x16x32_bf16 v[114:117], v[188:191], v[196:199], v[114:117]
	v_mfma_f32_16x16x32_bf16 v[102:105], v[180:183], v[204:207], v[102:105]
	v_mfma_f32_16x16x32_bf16 v[98:101], v[188:191], v[204:207], v[98:101]
	v_mfma_f32_16x16x32_bf16 v[86:89], v[180:183], v[212:215], v[86:89]
	v_mfma_f32_16x16x32_bf16 v[82:85], v[188:191], v[212:215], v[82:85]
	v_mfma_f32_16x16x32_bf16 v[70:73], v[180:183], v[224:227], v[70:73]
	v_mfma_f32_16x16x32_bf16 v[66:69], v[188:191], v[224:227], v[66:69]
	s_setprio 0
	s_barrier
	s_add_i32 s60, s66, s0
	v_lshl_add_u64 v[220:221], v[220:221], 0, s[26:27]
	s_mov_b32 m0, s60
	ds_read_b128 v[192:195], v161 offset:49152
	ds_read_b128 v[196:199], v161 offset:50176
	ds_read_b128 v[200:203], v161 offset:51200
	ds_read_b128 v[204:207], v161 offset:52224
	ds_read_b128 v[208:211], v161 offset:53248
	ds_read_b128 v[212:215], v161 offset:54272
	ds_read_b128 v[216:219], v161 offset:55296
	ds_read_b128 v[224:227], v161 offset:56320
	global_load_lds_dwordx4 v[220:221], off
	s_add_i32 m0, s60, 0x2000
	s_add_u32 s58, s58, 0x80080
	v_lshl_add_u64 v[220:221], v[222:223], 0, s[26:27]
	s_addc_u32 s59, s59, 0
	s_add_i32 s60, s67, s0
	global_load_lds_dwordx4 v[220:221], off
	v_lshl_add_u64 v[220:221], s[58:59], 0, v[132:133]
	s_mov_b32 m0, s60
	s_nop 0
	global_load_lds_dwordx4 v[220:221], off
	v_lshl_add_u64 v[220:221], s[58:59], 0, v[136:137]
	s_add_i32 m0, s60, 0x2000
	s_nop 0
	global_load_lds_dwordx4 v[220:221], off
	s_waitcnt vmcnt(6)
	s_waitcnt lgkmcnt(0)
	s_barrier
	s_setprio 1
	s_waitcnt lgkmcnt(0)
	v_mfma_f32_16x16x32_bf16 v[62:65], v[148:151], v[192:195], v[62:65]
	v_mfma_f32_16x16x32_bf16 v[58:61], v[168:171], v[192:195], v[58:61]
	v_mfma_f32_16x16x32_bf16 v[46:49], v[148:151], v[200:203], v[46:49]
	v_mfma_f32_16x16x32_bf16 v[42:45], v[168:171], v[200:203], v[42:45]
	v_mfma_f32_16x16x32_bf16 v[30:33], v[148:151], v[208:211], v[30:33]
	v_mfma_f32_16x16x32_bf16 v[26:29], v[168:171], v[208:211], v[26:29]
	v_mfma_f32_16x16x32_bf16 v[14:17], v[148:151], v[216:219], v[14:17]
	v_mfma_f32_16x16x32_bf16 v[10:13], v[168:171], v[216:219], v[10:13]
	v_mfma_f32_16x16x32_bf16 v[62:65], v[164:167], v[196:199], v[62:65]
	v_mfma_f32_16x16x32_bf16 v[58:61], v[172:175], v[196:199], v[58:61]
	v_mfma_f32_16x16x32_bf16 v[46:49], v[164:167], v[204:207], v[46:49]
	v_mfma_f32_16x16x32_bf16 v[42:45], v[172:175], v[204:207], v[42:45]
	v_mfma_f32_16x16x32_bf16 v[30:33], v[164:167], v[212:215], v[30:33]
	v_mfma_f32_16x16x32_bf16 v[26:29], v[172:175], v[212:215], v[26:29]
	v_mfma_f32_16x16x32_bf16 v[14:17], v[164:167], v[224:227], v[14:17]
	v_mfma_f32_16x16x32_bf16 v[10:13], v[172:175], v[224:227], v[10:13]
	s_setprio 0
	s_setprio 1
	v_mfma_f32_16x16x32_bf16 v[54:57], v[176:179], v[192:195], v[54:57]
	v_mfma_f32_16x16x32_bf16 v[50:53], v[184:187], v[192:195], v[50:53]
	v_mfma_f32_16x16x32_bf16 v[38:41], v[176:179], v[200:203], v[38:41]
	v_mfma_f32_16x16x32_bf16 v[34:37], v[184:187], v[200:203], v[34:37]
	v_mfma_f32_16x16x32_bf16 v[22:25], v[176:179], v[208:211], v[22:25]
	v_mfma_f32_16x16x32_bf16 v[18:21], v[184:187], v[208:211], v[18:21]
	v_mfma_f32_16x16x32_bf16 v[6:9], v[176:179], v[216:219], v[6:9]
	v_mfma_f32_16x16x32_bf16 v[2:5], v[184:187], v[216:219], v[2:5]
	v_mfma_f32_16x16x32_bf16 v[54:57], v[180:183], v[196:199], v[54:57]
	v_mfma_f32_16x16x32_bf16 v[50:53], v[188:191], v[196:199], v[50:53]
	v_mfma_f32_16x16x32_bf16 v[38:41], v[180:183], v[204:207], v[38:41]
	v_mfma_f32_16x16x32_bf16 v[34:37], v[188:191], v[204:207], v[34:37]
	v_mfma_f32_16x16x32_bf16 v[22:25], v[180:183], v[212:215], v[22:25]
	v_mfma_f32_16x16x32_bf16 v[18:21], v[188:191], v[212:215], v[18:21]
	v_mfma_f32_16x16x32_bf16 v[6:9], v[180:183], v[224:227], v[6:9]
	v_mfma_f32_16x16x32_bf16 v[2:5], v[188:191], v[224:227], v[2:5]
	s_setprio 0
	s_barrier
	s_add_i32 s65, s65, 2
	s_add_u32 s63, s63, 0x100
	s_addc_u32 s64, s64, 0
	s_add_u32 s46, s46, 0x100
	s_addc_u32 s47, s47, 0
	s_cmp_gt_u32 s65, 29
	s_cbranch_scc0 .LBB0_477
	s_and_b64 vcc, exec, s[28:29]
	s_cbranch_vccz .LBB0_480
	s_barrier

.LBB0_590:
	s_add_u32 s100, s58, 0xfff80000
	s_addc_u32 s101, s59, -1
	v_lshl_add_u64 v[222:223], s[100:101], 0, v[152:153]
	v_lshl_add_u64 v[236:237], s[100:101], 0, v[148:149]
	ds_read_b128 v[130:133], v198
	ds_read_b128 v[134:137], v198 offset:1024
	ds_read_b128 v[138:141], v198 offset:2048
	ds_read_b128 v[142:145], v198 offset:3072
	ds_read_b128 v[158:161], v199
	ds_read_b128 v[162:165], v199 offset:1024
	ds_read_b128 v[166:169], v199 offset:2048
	ds_read_b128 v[180:183], v199 offset:3072
	s_add_u32 s60, s58, 0xfff80080
	s_addc_u32 s61, s59, -1
	s_cmp_eq_u32 s75, 28
	s_cselect_b32 s63, s37, s61
	s_cselect_b32 s62, s71, s60
	s_cselect_b32 s61, s39, s74
	s_cselect_b32 s60, s72, s73
	v_lshl_add_u64 v[172:173], s[58:59], 0, v[156:157]
	ds_read_b128 v[186:189], v200
	ds_read_b128 v[190:193], v200 offset:1024
	ds_read_b128 v[194:197], v200 offset:2048
	ds_read_b128 v[214:217], v200 offset:3072
	ds_read_b128 v[218:221], v200 offset:4096
	ds_read_b128 v[224:227], v200 offset:5120
	ds_read_b128 v[228:231], v200 offset:6144
	ds_read_b128 v[232:235], v200 offset:7168
	s_mov_b32 m0, s68
	s_nop 0
	global_load_lds_dwordx4 v[222:223], off
	s_mov_b32 m0, s69
	s_nop 0
	global_load_lds_dwordx4 v[236:237], off
	s_add_i32 m0, s47, 0xc000
	s_nop 0
	global_load_lds_dwordx4 v[172:173], off
	v_lshl_add_u64 v[172:173], s[58:59], 0, v[154:155]
	s_add_i32 m0, s47, 0xe000
	s_nop 0
	global_load_lds_dwordx4 v[172:173], off
	s_waitcnt vmcnt(8)
	s_waitcnt lgkmcnt(0)
	s_barrier
	s_setprio 1
	s_waitcnt lgkmcnt(0)
	v_mfma_f32_16x16x32_bf16 v[126:129], v[130:133], v[186:189], v[126:129]
	v_mfma_f32_16x16x32_bf16 v[122:125], v[138:141], v[186:189], v[122:125]
	v_mfma_f32_16x16x32_bf16 v[118:121], v[130:133], v[194:197], v[118:121]
	v_mfma_f32_16x16x32_bf16 v[114:117], v[138:141], v[194:197], v[114:117]
	v_mfma_f32_16x16x32_bf16 v[110:113], v[130:133], v[218:221], v[110:113]
	v_mfma_f32_16x16x32_bf16 v[106:109], v[138:141], v[218:221], v[106:109]
	v_mfma_f32_16x16x32_bf16 v[102:105], v[130:133], v[228:231], v[102:105]
	v_mfma_f32_16x16x32_bf16 v[98:101], v[138:141], v[228:231], v[98:101]
	v_mfma_f32_16x16x32_bf16 v[126:129], v[134:137], v[190:193], v[126:129]
	v_mfma_f32_16x16x32_bf16 v[122:125], v[142:145], v[190:193], v[122:125]
	v_mfma_f32_16x16x32_bf16 v[118:121], v[134:137], v[214:217], v[118:121]
	v_mfma_f32_16x16x32_bf16 v[114:117], v[142:145], v[214:217], v[114:117]
	v_mfma_f32_16x16x32_bf16 v[110:113], v[134:137], v[224:227], v[110:113]
	v_mfma_f32_16x16x32_bf16 v[106:109], v[142:145], v[224:227], v[106:109]
	v_mfma_f32_16x16x32_bf16 v[102:105], v[134:137], v[232:235], v[102:105]
	v_mfma_f32_16x16x32_bf16 v[98:101], v[142:145], v[232:235], v[98:101]
	s_setprio 0
	s_setprio 1
	v_mfma_f32_16x16x32_bf16 v[70:73], v[158:161], v[186:189], v[70:73]
	v_mfma_f32_16x16x32_bf16 v[58:61], v[166:169], v[186:189], v[58:61]
	v_mfma_f32_16x16x32_bf16 v[54:57], v[158:161], v[194:197], v[54:57]
	v_mfma_f32_16x16x32_bf16 v[50:53], v[166:169], v[194:197], v[50:53]
	v_mfma_f32_16x16x32_bf16 v[46:49], v[158:161], v[218:221], v[46:49]
	v_mfma_f32_16x16x32_bf16 v[42:45], v[166:169], v[218:221], v[42:45]
	v_mfma_f32_16x16x32_bf16 v[38:41], v[158:161], v[228:231], v[38:41]
	v_mfma_f32_16x16x32_bf16 v[34:37], v[166:169], v[228:231], v[34:37]
	v_mfma_f32_16x16x32_bf16 v[70:73], v[162:165], v[190:193], v[70:73]
	v_mfma_f32_16x16x32_bf16 v[58:61], v[180:183], v[190:193], v[58:61]
	v_mfma_f32_16x16x32_bf16 v[54:57], v[162:165], v[214:217], v[54:57]
	v_mfma_f32_16x16x32_bf16 v[50:53], v[180:183], v[214:217], v[50:53]
	v_mfma_f32_16x16x32_bf16 v[46:49], v[162:165], v[224:227], v[46:49]
	v_mfma_f32_16x16x32_bf16 v[42:45], v[180:183], v[224:227], v[42:45]
	v_mfma_f32_16x16x32_bf16 v[38:41], v[162:165], v[232:235], v[38:41]
	v_mfma_f32_16x16x32_bf16 v[34:37], v[180:183], v[232:235], v[34:37]
	s_setprio 0
	s_barrier
	s_add_i32 s76, s0, s64
	v_lshl_add_u64 v[172:173], s[60:61], 0, v[150:151]
	s_mov_b32 m0, s76
	ds_read_b128 v[186:189], v200 offset:16384
	ds_read_b128 v[190:193], v200 offset:17408
	ds_read_b128 v[194:197], v200 offset:18432
	ds_read_b128 v[214:217], v200 offset:19456
	ds_read_b128 v[218:221], v200 offset:20480
	ds_read_b128 v[224:227], v200 offset:21504
	ds_read_b128 v[228:231], v200 offset:22528
	ds_read_b128 v[232:235], v200 offset:23552
	global_load_lds_dwordx4 v[172:173], off
	s_add_i32 m0, s76, 0x2000
	s_add_u32 s76, s60, 0x80000
	v_lshl_add_u64 v[176:177], s[60:61], 0, v[146:147]
	s_addc_u32 s77, s61, 0
	s_add_i32 s78, s1, s64
	global_load_lds_dwordx4 v[176:177], off
	v_lshl_add_u64 v[222:223], s[76:77], 0, v[150:151]
	s_mov_b32 m0, s78
	v_lshl_add_u64 v[236:237], s[62:63], 0, v[148:149]
	global_load_lds_dwordx4 v[222:223], off
	v_lshl_add_u64 v[222:223], s[76:77], 0, v[146:147]
	s_add_i32 m0, s78, 0x2000
	s_nop 0
	global_load_lds_dwordx4 v[222:223], off
	v_lshl_add_u64 v[222:223], s[62:63], 0, v[152:153]
	s_waitcnt vmcnt(6)
	s_waitcnt lgkmcnt(0)
	s_barrier
	s_setprio 1
	s_waitcnt lgkmcnt(0)
	v_mfma_f32_16x16x32_bf16 v[94:97], v[130:133], v[186:189], v[94:97]
	v_mfma_f32_16x16x32_bf16 v[90:93], v[138:141], v[186:189], v[90:93]
	v_mfma_f32_16x16x32_bf16 v[86:89], v[130:133], v[194:197], v[86:89]
	v_mfma_f32_16x16x32_bf16 v[82:85], v[138:141], v[194:197], v[82:85]
	v_mfma_f32_16x16x32_bf16 v[78:81], v[130:133], v[218:221], v[78:81]
	v_mfma_f32_16x16x32_bf16 v[74:77], v[138:141], v[218:221], v[74:77]
	v_mfma_f32_16x16x32_bf16 v[66:69], v[130:133], v[228:231], v[66:69]
	v_mfma_f32_16x16x32_bf16 v[62:65], v[138:141], v[228:231], v[62:65]
	v_mfma_f32_16x16x32_bf16 v[94:97], v[134:137], v[190:193], v[94:97]
	v_mfma_f32_16x16x32_bf16 v[90:93], v[142:145], v[190:193], v[90:93]
	v_mfma_f32_16x16x32_bf16 v[86:89], v[134:137], v[214:217], v[86:89]
	v_mfma_f32_16x16x32_bf16 v[82:85], v[142:145], v[214:217], v[82:85]
	v_mfma_f32_16x16x32_bf16 v[78:81], v[134:137], v[224:227], v[78:81]
	v_mfma_f32_16x16x32_bf16 v[74:77], v[142:145], v[224:227], v[74:77]
	v_mfma_f32_16x16x32_bf16 v[66:69], v[134:137], v[232:235], v[66:69]
	v_mfma_f32_16x16x32_bf16 v[62:65], v[142:145], v[232:235], v[62:65]
	s_setprio 0
	s_setprio 1
	v_mfma_f32_16x16x32_bf16 v[30:33], v[158:161], v[186:189], v[30:33]
	v_mfma_f32_16x16x32_bf16 v[26:29], v[166:169], v[186:189], v[26:29]
	v_mfma_f32_16x16x32_bf16 v[22:25], v[158:161], v[194:197], v[22:25]
	v_mfma_f32_16x16x32_bf16 v[18:21], v[166:169], v[194:197], v[18:21]
	v_mfma_f32_16x16x32_bf16 v[14:17], v[158:161], v[218:221], v[14:17]
	v_mfma_f32_16x16x32_bf16 v[10:13], v[166:169], v[218:221], v[10:13]
	v_mfma_f32_16x16x32_bf16 v[6:9], v[158:161], v[228:231], v[6:9]
	v_mfma_f32_16x16x32_bf16 v[2:5], v[166:169], v[228:231], v[2:5]
	v_mfma_f32_16x16x32_bf16 v[30:33], v[162:165], v[190:193], v[30:33]
	v_mfma_f32_16x16x32_bf16 v[26:29], v[180:183], v[190:193], v[26:29]
	v_mfma_f32_16x16x32_bf16 v[22:25], v[162:165], v[214:217], v[22:25]
	v_mfma_f32_16x16x32_bf16 v[18:21], v[180:183], v[214:217], v[18:21]
	v_mfma_f32_16x16x32_bf16 v[14:17], v[162:165], v[224:227], v[14:17]
	v_mfma_f32_16x16x32_bf16 v[10:13], v[180:183], v[224:227], v[10:13]
	v_mfma_f32_16x16x32_bf16 v[6:9], v[162:165], v[232:235], v[6:9]
	v_mfma_f32_16x16x32_bf16 v[2:5], v[180:183], v[232:235], v[2:5]
	s_setprio 0
	s_barrier
	v_add_u32_e32 v142, s33, v175
	v_add_u32_e32 v170, s48, v175
	ds_read_b128 v[130:133], v142
	ds_read_b128 v[134:137], v142 offset:1024
	ds_read_b128 v[138:141], v142 offset:2048
	ds_read_b128 v[142:145], v142 offset:3072
	ds_read_b128 v[158:161], v170
	ds_read_b128 v[162:165], v170 offset:1024
	ds_read_b128 v[166:169], v170 offset:2048
	ds_read_b128 v[180:183], v170 offset:3072
	s_add_u32 s62, s62, 0x80000
	s_addc_u32 s63, s63, 0
	v_lshl_add_u64 v[238:239], s[62:63], 0, v[152:153]
	ds_read_b128 v[186:189], v200 offset:32768
	ds_read_b128 v[190:193], v200 offset:33792
	ds_read_b128 v[194:197], v200 offset:34816
	ds_read_b128 v[214:217], v200 offset:35840
	ds_read_b128 v[218:221], v200 offset:36864
	ds_read_b128 v[224:227], v200 offset:37888
	ds_read_b128 v[228:231], v200 offset:38912
	ds_read_b128 v[232:235], v200 offset:39936
	s_mov_b32 m0, s47
	s_nop 0
	global_load_lds_dwordx4 v[222:223], off
	s_mov_b32 m0, s65
	s_nop 0
	global_load_lds_dwordx4 v[236:237], off
	s_mov_b32 m0, s66
	s_nop 0
	global_load_lds_dwordx4 v[238:239], off
	v_lshl_add_u64 v[238:239], s[62:63], 0, v[148:149]
	s_mov_b32 m0, s67
	s_nop 0
	global_load_lds_dwordx4 v[238:239], off
	s_waitcnt vmcnt(8)
	s_waitcnt lgkmcnt(0)
	s_barrier
	s_setprio 1
	s_waitcnt lgkmcnt(0)
	v_mfma_f32_16x16x32_bf16 v[126:129], v[130:133], v[186:189], v[126:129]
	v_mfma_f32_16x16x32_bf16 v[122:125], v[138:141], v[186:189], v[122:125]
	v_mfma_f32_16x16x32_bf16 v[118:121], v[130:133], v[194:197], v[118:121]
	v_mfma_f32_16x16x32_bf16 v[114:117], v[138:141], v[194:197], v[114:117]
	v_mfma_f32_16x16x32_bf16 v[110:113], v[130:133], v[218:221], v[110:113]
	v_mfma_f32_16x16x32_bf16 v[106:109], v[138:141], v[218:221], v[106:109]
	v_mfma_f32_16x16x32_bf16 v[102:105], v[130:133], v[228:231], v[102:105]
	v_mfma_f32_16x16x32_bf16 v[98:101], v[138:141], v[228:231], v[98:101]
	v_mfma_f32_16x16x32_bf16 v[126:129], v[134:137], v[190:193], v[126:129]
	v_mfma_f32_16x16x32_bf16 v[122:125], v[142:145], v[190:193], v[122:125]
	v_mfma_f32_16x16x32_bf16 v[118:121], v[134:137], v[214:217], v[118:121]
	v_mfma_f32_16x16x32_bf16 v[114:117], v[142:145], v[214:217], v[114:117]
	v_mfma_f32_16x16x32_bf16 v[110:113], v[134:137], v[224:227], v[110:113]
	v_mfma_f32_16x16x32_bf16 v[106:109], v[142:145], v[224:227], v[106:109]
	v_mfma_f32_16x16x32_bf16 v[102:105], v[134:137], v[232:235], v[102:105]
	v_mfma_f32_16x16x32_bf16 v[98:101], v[142:145], v[232:235], v[98:101]
	s_setprio 0
	s_setprio 1
	v_mfma_f32_16x16x32_bf16 v[70:73], v[158:161], v[186:189], v[70:73]
	v_mfma_f32_16x16x32_bf16 v[58:61], v[166:169], v[186:189], v[58:61]
	v_mfma_f32_16x16x32_bf16 v[54:57], v[158:161], v[194:197], v[54:57]
	v_mfma_f32_16x16x32_bf16 v[50:53], v[166:169], v[194:197], v[50:53]
	v_mfma_f32_16x16x32_bf16 v[46:49], v[158:161], v[218:221], v[46:49]
	v_mfma_f32_16x16x32_bf16 v[42:45], v[166:169], v[218:221], v[42:45]
	v_mfma_f32_16x16x32_bf16 v[38:41], v[158:161], v[228:231], v[38:41]
	v_mfma_f32_16x16x32_bf16 v[34:37], v[166:169], v[228:231], v[34:37]
	v_mfma_f32_16x16x32_bf16 v[70:73], v[162:165], v[190:193], v[70:73]
	v_mfma_f32_16x16x32_bf16 v[58:61], v[180:183], v[190:193], v[58:61]
	v_mfma_f32_16x16x32_bf16 v[54:57], v[162:165], v[214:217], v[54:57]
	v_mfma_f32_16x16x32_bf16 v[50:53], v[180:183], v[214:217], v[50:53]
	v_mfma_f32_16x16x32_bf16 v[46:49], v[162:165], v[224:227], v[46:49]
	v_mfma_f32_16x16x32_bf16 v[42:45], v[180:183], v[224:227], v[42:45]
	v_mfma_f32_16x16x32_bf16 v[38:41], v[162:165], v[232:235], v[38:41]
	v_mfma_f32_16x16x32_bf16 v[34:37], v[180:183], v[232:235], v[34:37]
	s_setprio 0
	s_barrier
	s_add_i32 s62, s33, s64
	v_lshl_add_u64 v[172:173], v[172:173], 0, s[28:29]
	s_mov_b32 m0, s62
	ds_read_b128 v[186:189], v200 offset:49152
	ds_read_b128 v[190:193], v200 offset:50176
	ds_read_b128 v[194:197], v200 offset:51200
	ds_read_b128 v[214:217], v200 offset:52224
	ds_read_b128 v[218:221], v200 offset:53248
	ds_read_b128 v[224:227], v200 offset:54272
	ds_read_b128 v[228:231], v200 offset:55296
	ds_read_b128 v[232:235], v200 offset:56320
	global_load_lds_dwordx4 v[172:173], off
	s_add_i32 m0, s62, 0x2000
	s_add_u32 s60, s60, 0x80080
	v_lshl_add_u64 v[172:173], v[176:177], 0, s[28:29]
	s_addc_u32 s61, s61, 0
	s_add_i32 s62, s48, s64
	global_load_lds_dwordx4 v[172:173], off
	v_lshl_add_u64 v[172:173], s[60:61], 0, v[150:151]
	s_mov_b32 m0, s62
	s_nop 0
	global_load_lds_dwordx4 v[172:173], off
	v_lshl_add_u64 v[172:173], s[60:61], 0, v[146:147]
	s_add_i32 m0, s62, 0x2000
	s_nop 0
	global_load_lds_dwordx4 v[172:173], off
	s_waitcnt vmcnt(6)
	s_waitcnt lgkmcnt(0)
	s_barrier
	s_setprio 1
	s_waitcnt lgkmcnt(0)
	v_mfma_f32_16x16x32_bf16 v[94:97], v[130:133], v[186:189], v[94:97]
	v_mfma_f32_16x16x32_bf16 v[90:93], v[138:141], v[186:189], v[90:93]
	v_mfma_f32_16x16x32_bf16 v[86:89], v[130:133], v[194:197], v[86:89]
	v_mfma_f32_16x16x32_bf16 v[82:85], v[138:141], v[194:197], v[82:85]
	v_mfma_f32_16x16x32_bf16 v[78:81], v[130:133], v[218:221], v[78:81]
	v_mfma_f32_16x16x32_bf16 v[74:77], v[138:141], v[218:221], v[74:77]
	v_mfma_f32_16x16x32_bf16 v[66:69], v[130:133], v[228:231], v[66:69]
	v_mfma_f32_16x16x32_bf16 v[62:65], v[138:141], v[228:231], v[62:65]
	v_mfma_f32_16x16x32_bf16 v[94:97], v[134:137], v[190:193], v[94:97]
	v_mfma_f32_16x16x32_bf16 v[90:93], v[142:145], v[190:193], v[90:93]
	v_mfma_f32_16x16x32_bf16 v[86:89], v[134:137], v[214:217], v[86:89]
	v_mfma_f32_16x16x32_bf16 v[82:85], v[142:145], v[214:217], v[82:85]
	v_mfma_f32_16x16x32_bf16 v[78:81], v[134:137], v[224:227], v[78:81]
	v_mfma_f32_16x16x32_bf16 v[74:77], v[142:145], v[224:227], v[74:77]
	v_mfma_f32_16x16x32_bf16 v[66:69], v[134:137], v[232:235], v[66:69]
	v_mfma_f32_16x16x32_bf16 v[62:65], v[142:145], v[232:235], v[62:65]
	s_setprio 0
	s_setprio 1
	v_mfma_f32_16x16x32_bf16 v[30:33], v[158:161], v[186:189], v[30:33]
	v_mfma_f32_16x16x32_bf16 v[26:29], v[166:169], v[186:189], v[26:29]
	v_mfma_f32_16x16x32_bf16 v[22:25], v[158:161], v[194:197], v[22:25]
	v_mfma_f32_16x16x32_bf16 v[18:21], v[166:169], v[194:197], v[18:21]
	v_mfma_f32_16x16x32_bf16 v[14:17], v[158:161], v[218:221], v[14:17]
	v_mfma_f32_16x16x32_bf16 v[10:13], v[166:169], v[218:221], v[10:13]
	v_mfma_f32_16x16x32_bf16 v[6:9], v[158:161], v[228:231], v[6:9]
	v_mfma_f32_16x16x32_bf16 v[2:5], v[166:169], v[228:231], v[2:5]
	v_mfma_f32_16x16x32_bf16 v[30:33], v[162:165], v[190:193], v[30:33]
	v_mfma_f32_16x16x32_bf16 v[26:29], v[180:183], v[190:193], v[26:29]
	v_mfma_f32_16x16x32_bf16 v[22:25], v[162:165], v[214:217], v[22:25]
	v_mfma_f32_16x16x32_bf16 v[18:21], v[180:183], v[214:217], v[18:21]
	v_mfma_f32_16x16x32_bf16 v[14:17], v[162:165], v[224:227], v[14:17]
	v_mfma_f32_16x16x32_bf16 v[10:13], v[180:183], v[224:227], v[10:13]
	v_mfma_f32_16x16x32_bf16 v[6:9], v[162:165], v[232:235], v[6:9]
	v_mfma_f32_16x16x32_bf16 v[2:5], v[180:183], v[232:235], v[2:5]
	s_setprio 0
	s_barrier
	s_add_i32 s75, s75, 2
	s_add_u32 s73, s73, 0x100
	s_addc_u32 s74, s74, 0
	s_add_u32 s58, s58, 0x100
	s_addc_u32 s59, s59, 0
	s_cmp_gt_u32 s75, 29
	s_cbranch_scc0 .LBB0_590
	s_and_b64 vcc, exec, s[30:31]
	s_cbranch_vccz .LBB0_593
	s_barrier

.LBB0_633:
	s_add_u32 s100, s58, 0xffe00000
	s_addc_u32 s101, s59, -1
	v_lshl_add_u64 v[222:223], s[100:101], 0, v[130:131]
	v_lshl_add_u64 v[224:225], s[100:101], 0, v[134:135]
	ds_read_b128 v[144:147], v160
	ds_read_b128 v[148:151], v160 offset:1024
	ds_read_b128 v[164:167], v160 offset:2048
	ds_read_b128 v[168:171], v160 offset:3072
	ds_read_b128 v[172:175], v161
	ds_read_b128 v[176:179], v161 offset:1024
	ds_read_b128 v[180:183], v161 offset:2048
	ds_read_b128 v[184:187], v161 offset:3072
	s_add_u32 s60, s58, 0xffe00080
	s_addc_u32 s61, s59, -1
	s_cmpk_eq_i32 s73, 0x7c
	s_cselect_b32 s63, s37, s61
	s_cselect_b32 s62, s45, s60
	s_cselect_b32 s61, s39, s72
	s_cselect_b32 s60, s70, s71
	v_lshl_add_u64 v[152:153], s[58:59], 0, v[142:143]
	ds_read_b128 v[188:191], v162
	ds_read_b128 v[192:195], v162 offset:1024
	ds_read_b128 v[196:199], v162 offset:2048
	ds_read_b128 v[200:203], v162 offset:3072
	ds_read_b128 v[204:207], v162 offset:4096
	ds_read_b128 v[208:211], v162 offset:5120
	ds_read_b128 v[212:215], v162 offset:6144
	ds_read_b128 v[216:219], v162 offset:7168
	s_mov_b32 m0, s66
	s_nop 0
	global_load_lds_dwordx4 v[222:223], off
	s_mov_b32 m0, s67
	s_nop 0
	global_load_lds_dwordx4 v[224:225], off
	s_add_i32 m0, s47, 0xc000
	s_nop 0
	global_load_lds_dwordx4 v[152:153], off
	v_lshl_add_u64 v[152:153], s[58:59], 0, v[140:141]
	s_add_i32 m0, s47, 0xe000
	s_nop 0
	global_load_lds_dwordx4 v[152:153], off
	s_waitcnt vmcnt(8)
	s_waitcnt lgkmcnt(0)
	s_barrier
	s_setprio 1
	s_waitcnt lgkmcnt(0)
	v_mfma_f32_16x16x32_bf16 v[126:129], v[144:147], v[188:191], v[126:129]
	v_mfma_f32_16x16x32_bf16 v[122:125], v[164:167], v[188:191], v[122:125]
	v_mfma_f32_16x16x32_bf16 v[110:113], v[144:147], v[196:199], v[110:113]
	v_mfma_f32_16x16x32_bf16 v[106:109], v[164:167], v[196:199], v[106:109]
	v_mfma_f32_16x16x32_bf16 v[94:97], v[144:147], v[204:207], v[94:97]
	v_mfma_f32_16x16x32_bf16 v[90:93], v[164:167], v[204:207], v[90:93]
	v_mfma_f32_16x16x32_bf16 v[78:81], v[144:147], v[212:215], v[78:81]
	v_mfma_f32_16x16x32_bf16 v[74:77], v[164:167], v[212:215], v[74:77]
	v_mfma_f32_16x16x32_bf16 v[126:129], v[148:151], v[192:195], v[126:129]
	v_mfma_f32_16x16x32_bf16 v[122:125], v[168:171], v[192:195], v[122:125]
	v_mfma_f32_16x16x32_bf16 v[110:113], v[148:151], v[200:203], v[110:113]
	v_mfma_f32_16x16x32_bf16 v[106:109], v[168:171], v[200:203], v[106:109]
	v_mfma_f32_16x16x32_bf16 v[94:97], v[148:151], v[208:211], v[94:97]
	v_mfma_f32_16x16x32_bf16 v[90:93], v[168:171], v[208:211], v[90:93]
	v_mfma_f32_16x16x32_bf16 v[78:81], v[148:151], v[216:219], v[78:81]
	v_mfma_f32_16x16x32_bf16 v[74:77], v[168:171], v[216:219], v[74:77]
	s_setprio 0
	s_setprio 1
	v_mfma_f32_16x16x32_bf16 v[118:121], v[172:175], v[188:191], v[118:121]
	v_mfma_f32_16x16x32_bf16 v[114:117], v[180:183], v[188:191], v[114:117]
	v_mfma_f32_16x16x32_bf16 v[102:105], v[172:175], v[196:199], v[102:105]
	v_mfma_f32_16x16x32_bf16 v[98:101], v[180:183], v[196:199], v[98:101]
	v_mfma_f32_16x16x32_bf16 v[86:89], v[172:175], v[204:207], v[86:89]
	v_mfma_f32_16x16x32_bf16 v[82:85], v[180:183], v[204:207], v[82:85]
	v_mfma_f32_16x16x32_bf16 v[70:73], v[172:175], v[212:215], v[70:73]
	v_mfma_f32_16x16x32_bf16 v[66:69], v[180:183], v[212:215], v[66:69]
	v_mfma_f32_16x16x32_bf16 v[118:121], v[176:179], v[192:195], v[118:121]
	v_mfma_f32_16x16x32_bf16 v[114:117], v[184:187], v[192:195], v[114:117]
	v_mfma_f32_16x16x32_bf16 v[102:105], v[176:179], v[200:203], v[102:105]
	v_mfma_f32_16x16x32_bf16 v[98:101], v[184:187], v[200:203], v[98:101]
	v_mfma_f32_16x16x32_bf16 v[86:89], v[176:179], v[208:211], v[86:89]
	v_mfma_f32_16x16x32_bf16 v[82:85], v[184:187], v[208:211], v[82:85]
	v_mfma_f32_16x16x32_bf16 v[70:73], v[176:179], v[216:219], v[70:73]
	v_mfma_f32_16x16x32_bf16 v[66:69], v[184:187], v[216:219], v[66:69]
	s_setprio 0
	s_barrier
	s_add_i32 s74, s0, s53
	v_lshl_add_u64 v[152:153], s[60:61], 0, v[132:133]
	s_mov_b32 m0, s74
	ds_read_b128 v[188:191], v162 offset:16384
	ds_read_b128 v[192:195], v162 offset:17408
	ds_read_b128 v[196:199], v162 offset:18432
	ds_read_b128 v[200:203], v162 offset:19456
	ds_read_b128 v[204:207], v162 offset:20480
	ds_read_b128 v[208:211], v162 offset:21504
	ds_read_b128 v[212:215], v162 offset:22528
	ds_read_b128 v[216:219], v162 offset:23552
	global_load_lds_dwordx4 v[152:153], off
	s_add_i32 m0, s74, 0x2000
	s_add_u32 s74, s60, 0x200000
	v_lshl_add_u64 v[220:221], s[60:61], 0, v[136:137]
	s_addc_u32 s75, s61, 0
	s_add_i32 s76, s1, s53
	global_load_lds_dwordx4 v[220:221], off
	v_lshl_add_u64 v[222:223], s[74:75], 0, v[132:133]
	s_mov_b32 m0, s76
	v_lshl_add_u64 v[224:225], s[62:63], 0, v[134:135]
	global_load_lds_dwordx4 v[222:223], off
	v_lshl_add_u64 v[222:223], s[74:75], 0, v[136:137]
	s_add_i32 m0, s76, 0x2000
	s_nop 0
	global_load_lds_dwordx4 v[222:223], off
	v_lshl_add_u64 v[222:223], s[62:63], 0, v[130:131]
	s_waitcnt vmcnt(6)
	s_waitcnt lgkmcnt(0)
	s_barrier
	s_setprio 1
	s_waitcnt lgkmcnt(0)
	v_mfma_f32_16x16x32_bf16 v[62:65], v[144:147], v[188:191], v[62:65]
	v_mfma_f32_16x16x32_bf16 v[58:61], v[164:167], v[188:191], v[58:61]
	v_mfma_f32_16x16x32_bf16 v[46:49], v[144:147], v[196:199], v[46:49]
	v_mfma_f32_16x16x32_bf16 v[42:45], v[164:167], v[196:199], v[42:45]
	v_mfma_f32_16x16x32_bf16 v[30:33], v[144:147], v[204:207], v[30:33]
	v_mfma_f32_16x16x32_bf16 v[26:29], v[164:167], v[204:207], v[26:29]
	v_mfma_f32_16x16x32_bf16 v[14:17], v[144:147], v[212:215], v[14:17]
	v_mfma_f32_16x16x32_bf16 v[10:13], v[164:167], v[212:215], v[10:13]
	v_mfma_f32_16x16x32_bf16 v[62:65], v[148:151], v[192:195], v[62:65]
	v_mfma_f32_16x16x32_bf16 v[58:61], v[168:171], v[192:195], v[58:61]
	v_mfma_f32_16x16x32_bf16 v[46:49], v[148:151], v[200:203], v[46:49]
	v_mfma_f32_16x16x32_bf16 v[42:45], v[168:171], v[200:203], v[42:45]
	v_mfma_f32_16x16x32_bf16 v[30:33], v[148:151], v[208:211], v[30:33]
	v_mfma_f32_16x16x32_bf16 v[26:29], v[168:171], v[208:211], v[26:29]
	v_mfma_f32_16x16x32_bf16 v[14:17], v[148:151], v[216:219], v[14:17]
	v_mfma_f32_16x16x32_bf16 v[10:13], v[168:171], v[216:219], v[10:13]
	s_setprio 0
	s_setprio 1
	v_mfma_f32_16x16x32_bf16 v[54:57], v[172:175], v[188:191], v[54:57]
	v_mfma_f32_16x16x32_bf16 v[50:53], v[180:183], v[188:191], v[50:53]
	v_mfma_f32_16x16x32_bf16 v[38:41], v[172:175], v[196:199], v[38:41]
	v_mfma_f32_16x16x32_bf16 v[34:37], v[180:183], v[196:199], v[34:37]
	v_mfma_f32_16x16x32_bf16 v[22:25], v[172:175], v[204:207], v[22:25]
	v_mfma_f32_16x16x32_bf16 v[18:21], v[180:183], v[204:207], v[18:21]
	v_mfma_f32_16x16x32_bf16 v[6:9], v[172:175], v[212:215], v[6:9]
	v_mfma_f32_16x16x32_bf16 v[2:5], v[180:183], v[212:215], v[2:5]
	v_mfma_f32_16x16x32_bf16 v[54:57], v[176:179], v[192:195], v[54:57]
	v_mfma_f32_16x16x32_bf16 v[50:53], v[184:187], v[192:195], v[50:53]
	v_mfma_f32_16x16x32_bf16 v[38:41], v[176:179], v[200:203], v[38:41]
	v_mfma_f32_16x16x32_bf16 v[34:37], v[184:187], v[200:203], v[34:37]
	v_mfma_f32_16x16x32_bf16 v[22:25], v[176:179], v[208:211], v[22:25]
	v_mfma_f32_16x16x32_bf16 v[18:21], v[184:187], v[208:211], v[18:21]
	v_mfma_f32_16x16x32_bf16 v[6:9], v[176:179], v[216:219], v[6:9]
	v_mfma_f32_16x16x32_bf16 v[2:5], v[184:187], v[216:219], v[2:5]
	s_setprio 0
	s_barrier
	v_add_u32_e32 v168, s33, v155
	v_add_u32_e32 v184, s48, v155
	ds_read_b128 v[144:147], v168
	ds_read_b128 v[148:151], v168 offset:1024
	ds_read_b128 v[164:167], v168 offset:2048
	ds_read_b128 v[168:171], v168 offset:3072
	ds_read_b128 v[172:175], v184
	ds_read_b128 v[176:179], v184 offset:1024
	ds_read_b128 v[180:183], v184 offset:2048
	ds_read_b128 v[184:187], v184 offset:3072
	s_add_u32 s62, s62, 0x200000
	s_addc_u32 s63, s63, 0
	v_lshl_add_u64 v[226:227], s[62:63], 0, v[130:131]
	ds_read_b128 v[188:191], v162 offset:32768
	ds_read_b128 v[192:195], v162 offset:33792
	ds_read_b128 v[196:199], v162 offset:34816
	ds_read_b128 v[200:203], v162 offset:35840
	ds_read_b128 v[204:207], v162 offset:36864
	ds_read_b128 v[208:211], v162 offset:37888
	ds_read_b128 v[212:215], v162 offset:38912
	ds_read_b128 v[216:219], v162 offset:39936
	s_mov_b32 m0, s47
	s_nop 0
	global_load_lds_dwordx4 v[222:223], off
	s_mov_b32 m0, s56
	s_nop 0
	global_load_lds_dwordx4 v[224:225], off
	s_mov_b32 m0, s57
	s_nop 0
	global_load_lds_dwordx4 v[226:227], off
	v_lshl_add_u64 v[226:227], s[62:63], 0, v[134:135]
	s_mov_b32 m0, s64
	s_nop 0
	global_load_lds_dwordx4 v[226:227], off
	s_waitcnt vmcnt(8)
	s_waitcnt lgkmcnt(0)
	s_barrier
	s_setprio 1
	s_waitcnt lgkmcnt(0)
	v_mfma_f32_16x16x32_bf16 v[126:129], v[144:147], v[188:191], v[126:129]
	v_mfma_f32_16x16x32_bf16 v[122:125], v[164:167], v[188:191], v[122:125]
	v_mfma_f32_16x16x32_bf16 v[110:113], v[144:147], v[196:199], v[110:113]
	v_mfma_f32_16x16x32_bf16 v[106:109], v[164:167], v[196:199], v[106:109]
	v_mfma_f32_16x16x32_bf16 v[94:97], v[144:147], v[204:207], v[94:97]
	v_mfma_f32_16x16x32_bf16 v[90:93], v[164:167], v[204:207], v[90:93]
	v_mfma_f32_16x16x32_bf16 v[78:81], v[144:147], v[212:215], v[78:81]
	v_mfma_f32_16x16x32_bf16 v[74:77], v[164:167], v[212:215], v[74:77]
	v_mfma_f32_16x16x32_bf16 v[126:129], v[148:151], v[192:195], v[126:129]
	v_mfma_f32_16x16x32_bf16 v[122:125], v[168:171], v[192:195], v[122:125]
	v_mfma_f32_16x16x32_bf16 v[110:113], v[148:151], v[200:203], v[110:113]
	v_mfma_f32_16x16x32_bf16 v[106:109], v[168:171], v[200:203], v[106:109]
	v_mfma_f32_16x16x32_bf16 v[94:97], v[148:151], v[208:211], v[94:97]
	v_mfma_f32_16x16x32_bf16 v[90:93], v[168:171], v[208:211], v[90:93]
	v_mfma_f32_16x16x32_bf16 v[78:81], v[148:151], v[216:219], v[78:81]
	v_mfma_f32_16x16x32_bf16 v[74:77], v[168:171], v[216:219], v[74:77]
	s_setprio 0
	s_setprio 1
	v_mfma_f32_16x16x32_bf16 v[118:121], v[172:175], v[188:191], v[118:121]
	v_mfma_f32_16x16x32_bf16 v[114:117], v[180:183], v[188:191], v[114:117]
	v_mfma_f32_16x16x32_bf16 v[102:105], v[172:175], v[196:199], v[102:105]
	v_mfma_f32_16x16x32_bf16 v[98:101], v[180:183], v[196:199], v[98:101]
	v_mfma_f32_16x16x32_bf16 v[86:89], v[172:175], v[204:207], v[86:89]
	v_mfma_f32_16x16x32_bf16 v[82:85], v[180:183], v[204:207], v[82:85]
	v_mfma_f32_16x16x32_bf16 v[70:73], v[172:175], v[212:215], v[70:73]
	v_mfma_f32_16x16x32_bf16 v[66:69], v[180:183], v[212:215], v[66:69]
	v_mfma_f32_16x16x32_bf16 v[118:121], v[176:179], v[192:195], v[118:121]
	v_mfma_f32_16x16x32_bf16 v[114:117], v[184:187], v[192:195], v[114:117]
	v_mfma_f32_16x16x32_bf16 v[102:105], v[176:179], v[200:203], v[102:105]
	v_mfma_f32_16x16x32_bf16 v[98:101], v[184:187], v[200:203], v[98:101]
	v_mfma_f32_16x16x32_bf16 v[86:89], v[176:179], v[208:211], v[86:89]
	v_mfma_f32_16x16x32_bf16 v[82:85], v[184:187], v[208:211], v[82:85]
	v_mfma_f32_16x16x32_bf16 v[70:73], v[176:179], v[216:219], v[70:73]
	v_mfma_f32_16x16x32_bf16 v[66:69], v[184:187], v[216:219], v[66:69]
	s_setprio 0
	s_barrier
	s_add_i32 s62, s33, s53
	v_lshl_add_u64 v[152:153], v[152:153], 0, s[28:29]
	s_mov_b32 m0, s62
	ds_read_b128 v[188:191], v162 offset:49152
	ds_read_b128 v[192:195], v162 offset:50176
	ds_read_b128 v[196:199], v162 offset:51200
	ds_read_b128 v[200:203], v162 offset:52224
	ds_read_b128 v[204:207], v162 offset:53248
	ds_read_b128 v[208:211], v162 offset:54272
	ds_read_b128 v[212:215], v162 offset:55296
	ds_read_b128 v[216:219], v162 offset:56320
	global_load_lds_dwordx4 v[152:153], off
	s_add_i32 m0, s62, 0x2000
	s_add_u32 s60, s60, 0x200080
	v_lshl_add_u64 v[152:153], v[220:221], 0, s[28:29]
	s_addc_u32 s61, s61, 0
	s_add_i32 s62, s48, s53
	global_load_lds_dwordx4 v[152:153], off
	v_lshl_add_u64 v[152:153], s[60:61], 0, v[132:133]
	s_mov_b32 m0, s62
	s_nop 0
	global_load_lds_dwordx4 v[152:153], off
	v_lshl_add_u64 v[152:153], s[60:61], 0, v[136:137]
	s_add_i32 m0, s62, 0x2000
	s_nop 0
	global_load_lds_dwordx4 v[152:153], off
	s_waitcnt vmcnt(6)
	s_waitcnt lgkmcnt(0)
	s_barrier
	s_setprio 1
	s_waitcnt lgkmcnt(0)
	v_mfma_f32_16x16x32_bf16 v[62:65], v[144:147], v[188:191], v[62:65]
	v_mfma_f32_16x16x32_bf16 v[58:61], v[164:167], v[188:191], v[58:61]
	v_mfma_f32_16x16x32_bf16 v[46:49], v[144:147], v[196:199], v[46:49]
	v_mfma_f32_16x16x32_bf16 v[42:45], v[164:167], v[196:199], v[42:45]
	v_mfma_f32_16x16x32_bf16 v[30:33], v[144:147], v[204:207], v[30:33]
	v_mfma_f32_16x16x32_bf16 v[26:29], v[164:167], v[204:207], v[26:29]
	v_mfma_f32_16x16x32_bf16 v[14:17], v[144:147], v[212:215], v[14:17]
	v_mfma_f32_16x16x32_bf16 v[10:13], v[164:167], v[212:215], v[10:13]
	v_mfma_f32_16x16x32_bf16 v[62:65], v[148:151], v[192:195], v[62:65]
	v_mfma_f32_16x16x32_bf16 v[58:61], v[168:171], v[192:195], v[58:61]
	v_mfma_f32_16x16x32_bf16 v[46:49], v[148:151], v[200:203], v[46:49]
	v_mfma_f32_16x16x32_bf16 v[42:45], v[168:171], v[200:203], v[42:45]
	v_mfma_f32_16x16x32_bf16 v[30:33], v[148:151], v[208:211], v[30:33]
	v_mfma_f32_16x16x32_bf16 v[26:29], v[168:171], v[208:211], v[26:29]
	v_mfma_f32_16x16x32_bf16 v[14:17], v[148:151], v[216:219], v[14:17]
	v_mfma_f32_16x16x32_bf16 v[10:13], v[168:171], v[216:219], v[10:13]
	s_setprio 0
	s_setprio 1
	v_mfma_f32_16x16x32_bf16 v[54:57], v[172:175], v[188:191], v[54:57]
	v_mfma_f32_16x16x32_bf16 v[50:53], v[180:183], v[188:191], v[50:53]
	v_mfma_f32_16x16x32_bf16 v[38:41], v[172:175], v[196:199], v[38:41]
	v_mfma_f32_16x16x32_bf16 v[34:37], v[180:183], v[196:199], v[34:37]
	v_mfma_f32_16x16x32_bf16 v[22:25], v[172:175], v[204:207], v[22:25]
	v_mfma_f32_16x16x32_bf16 v[18:21], v[180:183], v[204:207], v[18:21]
	v_mfma_f32_16x16x32_bf16 v[6:9], v[172:175], v[212:215], v[6:9]
	v_mfma_f32_16x16x32_bf16 v[2:5], v[180:183], v[212:215], v[2:5]
	v_mfma_f32_16x16x32_bf16 v[54:57], v[176:179], v[192:195], v[54:57]
	v_mfma_f32_16x16x32_bf16 v[50:53], v[184:187], v[192:195], v[50:53]
	v_mfma_f32_16x16x32_bf16 v[38:41], v[176:179], v[200:203], v[38:41]
	v_mfma_f32_16x16x32_bf16 v[34:37], v[184:187], v[200:203], v[34:37]
	v_mfma_f32_16x16x32_bf16 v[22:25], v[176:179], v[208:211], v[22:25]
	v_mfma_f32_16x16x32_bf16 v[18:21], v[184:187], v[208:211], v[18:21]
	v_mfma_f32_16x16x32_bf16 v[6:9], v[176:179], v[216:219], v[6:9]
	v_mfma_f32_16x16x32_bf16 v[2:5], v[184:187], v[216:219], v[2:5]
	s_setprio 0
	s_barrier
	s_add_i32 s73, s73, 2
	s_add_u32 s71, s71, 0x100
	s_addc_u32 s72, s72, 0
	s_add_u32 s58, s58, 0x100
	s_addc_u32 s59, s59, 0
	s_cmpk_gt_u32 s73, 0x7d
	s_cbranch_scc0 .LBB0_633
	s_and_b64 vcc, exec, s[30:31]
	s_cbranch_vccz .LBB0_636
	s_barrier

.LBB0_848:
	s_add_u32 s100, s10, 0xfff80000
	s_addc_u32 s101, s11, -1
	v_lshl_add_u64 v[220:221], s[100:101], 0, v[130:131]
	v_lshl_add_u64 v[222:223], s[100:101], 0, v[132:133]
	ds_read_b128 v[142:145], v171
	ds_read_b128 v[146:149], v171 offset:1024
	ds_read_b128 v[150:153], v171 offset:2048
	ds_read_b128 v[154:157], v171 offset:3072
	ds_read_b128 v[158:161], v172
	ds_read_b128 v[174:177], v172 offset:1024
	ds_read_b128 v[178:181], v172 offset:2048
	ds_read_b128 v[182:185], v172 offset:3072
	s_add_u32 s68, s10, 0xfff80080
	s_addc_u32 s69, s11, -1
	s_cmp_eq_u32 s81, 28
	s_cselect_b32 s71, s13, s69
	s_cselect_b32 s70, s59, s68
	s_cselect_b32 s69, s61, s80
	s_cselect_b32 s68, s67, s79
	v_lshl_add_u64 v[162:163], s[10:11], 0, v[136:137]
	ds_read_b128 v[186:189], v173
	ds_read_b128 v[190:193], v173 offset:1024
	ds_read_b128 v[194:197], v173 offset:2048
	ds_read_b128 v[198:201], v173 offset:3072
	ds_read_b128 v[202:205], v173 offset:4096
	ds_read_b128 v[206:209], v173 offset:5120
	ds_read_b128 v[210:213], v173 offset:6144
	ds_read_b128 v[214:217], v173 offset:7168
	s_mov_b32 m0, s76
	s_nop 0
	global_load_lds_dwordx4 v[220:221], off
	s_mov_b32 m0, s77
	s_nop 0
	global_load_lds_dwordx4 v[222:223], off
	s_add_i32 m0, s51, 0xc000
	s_nop 0
	global_load_lds_dwordx4 v[162:163], off
	v_lshl_add_u64 v[162:163], s[10:11], 0, v[134:135]
	s_add_i32 m0, s51, 0xe000
	s_nop 0
	global_load_lds_dwordx4 v[162:163], off
	s_waitcnt vmcnt(8)
	s_waitcnt lgkmcnt(0)
	s_barrier
	s_setprio 1
	s_waitcnt lgkmcnt(0)
	v_mfma_f32_16x16x32_bf16 v[126:129], v[142:145], v[186:189], v[126:129]
	v_mfma_f32_16x16x32_bf16 v[122:125], v[150:153], v[186:189], v[122:125]
	v_mfma_f32_16x16x32_bf16 v[110:113], v[142:145], v[194:197], v[110:113]
	v_mfma_f32_16x16x32_bf16 v[106:109], v[150:153], v[194:197], v[106:109]
	v_mfma_f32_16x16x32_bf16 v[94:97], v[142:145], v[202:205], v[94:97]
	v_mfma_f32_16x16x32_bf16 v[90:93], v[150:153], v[202:205], v[90:93]
	v_mfma_f32_16x16x32_bf16 v[78:81], v[142:145], v[210:213], v[78:81]
	v_mfma_f32_16x16x32_bf16 v[74:77], v[150:153], v[210:213], v[74:77]
	v_mfma_f32_16x16x32_bf16 v[126:129], v[146:149], v[190:193], v[126:129]
	v_mfma_f32_16x16x32_bf16 v[122:125], v[154:157], v[190:193], v[122:125]
	v_mfma_f32_16x16x32_bf16 v[110:113], v[146:149], v[198:201], v[110:113]
	v_mfma_f32_16x16x32_bf16 v[106:109], v[154:157], v[198:201], v[106:109]
	v_mfma_f32_16x16x32_bf16 v[94:97], v[146:149], v[206:209], v[94:97]
	v_mfma_f32_16x16x32_bf16 v[90:93], v[154:157], v[206:209], v[90:93]
	v_mfma_f32_16x16x32_bf16 v[78:81], v[146:149], v[214:217], v[78:81]
	v_mfma_f32_16x16x32_bf16 v[74:77], v[154:157], v[214:217], v[74:77]
	s_setprio 0
	s_setprio 1
	v_mfma_f32_16x16x32_bf16 v[118:121], v[158:161], v[186:189], v[118:121]
	v_mfma_f32_16x16x32_bf16 v[114:117], v[178:181], v[186:189], v[114:117]
	v_mfma_f32_16x16x32_bf16 v[102:105], v[158:161], v[194:197], v[102:105]
	v_mfma_f32_16x16x32_bf16 v[98:101], v[178:181], v[194:197], v[98:101]
	v_mfma_f32_16x16x32_bf16 v[86:89], v[158:161], v[202:205], v[86:89]
	v_mfma_f32_16x16x32_bf16 v[82:85], v[178:181], v[202:205], v[82:85]
	v_mfma_f32_16x16x32_bf16 v[70:73], v[158:161], v[210:213], v[70:73]
	v_mfma_f32_16x16x32_bf16 v[66:69], v[178:181], v[210:213], v[66:69]
	v_mfma_f32_16x16x32_bf16 v[118:121], v[174:177], v[190:193], v[118:121]
	v_mfma_f32_16x16x32_bf16 v[114:117], v[182:185], v[190:193], v[114:117]
	v_mfma_f32_16x16x32_bf16 v[102:105], v[174:177], v[198:201], v[102:105]
	v_mfma_f32_16x16x32_bf16 v[98:101], v[182:185], v[198:201], v[98:101]
	v_mfma_f32_16x16x32_bf16 v[86:89], v[174:177], v[206:209], v[86:89]
	v_mfma_f32_16x16x32_bf16 v[82:85], v[182:185], v[206:209], v[82:85]
	v_mfma_f32_16x16x32_bf16 v[70:73], v[174:177], v[214:217], v[70:73]
	v_mfma_f32_16x16x32_bf16 v[66:69], v[182:185], v[214:217], v[66:69]
	s_setprio 0
	s_barrier
	s_add_i32 s82, s3, s49
	v_lshl_add_u64 v[162:163], s[68:69], 0, v[130:131]
	s_mov_b32 m0, s82
	ds_read_b128 v[186:189], v173 offset:16384
	ds_read_b128 v[190:193], v173 offset:17408
	ds_read_b128 v[194:197], v173 offset:18432
	ds_read_b128 v[198:201], v173 offset:19456
	ds_read_b128 v[202:205], v173 offset:20480
	ds_read_b128 v[206:209], v173 offset:21504
	ds_read_b128 v[210:213], v173 offset:22528
	ds_read_b128 v[214:217], v173 offset:23552
	global_load_lds_dwordx4 v[162:163], off
	s_add_i32 m0, s82, 0x2000
	s_add_u32 s82, s68, 0x80000
	v_lshl_add_u64 v[218:219], s[68:69], 0, v[132:133]
	s_addc_u32 s83, s69, 0
	s_add_i32 s84, s45, s49
	global_load_lds_dwordx4 v[218:219], off
	v_lshl_add_u64 v[220:221], s[82:83], 0, v[130:131]
	s_mov_b32 m0, s84
	v_lshl_add_u64 v[222:223], s[70:71], 0, v[132:133]
	global_load_lds_dwordx4 v[220:221], off
	v_lshl_add_u64 v[220:221], s[82:83], 0, v[132:133]
	s_add_i32 m0, s84, 0x2000
	s_nop 0
	global_load_lds_dwordx4 v[220:221], off
	v_lshl_add_u64 v[220:221], s[70:71], 0, v[130:131]
	s_waitcnt vmcnt(6)
	s_waitcnt lgkmcnt(0)
	s_barrier
	s_setprio 1
	s_waitcnt lgkmcnt(0)
	v_mfma_f32_16x16x32_bf16 v[62:65], v[142:145], v[186:189], v[62:65]
	v_mfma_f32_16x16x32_bf16 v[58:61], v[150:153], v[186:189], v[58:61]
	v_mfma_f32_16x16x32_bf16 v[46:49], v[142:145], v[194:197], v[46:49]
	v_mfma_f32_16x16x32_bf16 v[42:45], v[150:153], v[194:197], v[42:45]
	v_mfma_f32_16x16x32_bf16 v[30:33], v[142:145], v[202:205], v[30:33]
	v_mfma_f32_16x16x32_bf16 v[26:29], v[150:153], v[202:205], v[26:29]
	v_mfma_f32_16x16x32_bf16 v[14:17], v[142:145], v[210:213], v[14:17]
	v_mfma_f32_16x16x32_bf16 v[10:13], v[150:153], v[210:213], v[10:13]
	v_mfma_f32_16x16x32_bf16 v[62:65], v[146:149], v[190:193], v[62:65]
	v_mfma_f32_16x16x32_bf16 v[58:61], v[154:157], v[190:193], v[58:61]
	v_mfma_f32_16x16x32_bf16 v[46:49], v[146:149], v[198:201], v[46:49]
	v_mfma_f32_16x16x32_bf16 v[42:45], v[154:157], v[198:201], v[42:45]
	v_mfma_f32_16x16x32_bf16 v[30:33], v[146:149], v[206:209], v[30:33]
	v_mfma_f32_16x16x32_bf16 v[26:29], v[154:157], v[206:209], v[26:29]
	v_mfma_f32_16x16x32_bf16 v[14:17], v[146:149], v[214:217], v[14:17]
	v_mfma_f32_16x16x32_bf16 v[10:13], v[154:157], v[214:217], v[10:13]
	s_setprio 0
	s_setprio 1
	v_mfma_f32_16x16x32_bf16 v[54:57], v[158:161], v[186:189], v[54:57]
	v_mfma_f32_16x16x32_bf16 v[50:53], v[178:181], v[186:189], v[50:53]
	v_mfma_f32_16x16x32_bf16 v[38:41], v[158:161], v[194:197], v[38:41]
	v_mfma_f32_16x16x32_bf16 v[34:37], v[178:181], v[194:197], v[34:37]
	v_mfma_f32_16x16x32_bf16 v[22:25], v[158:161], v[202:205], v[22:25]
	v_mfma_f32_16x16x32_bf16 v[18:21], v[178:181], v[202:205], v[18:21]
	v_mfma_f32_16x16x32_bf16 v[6:9], v[158:161], v[210:213], v[6:9]
	v_mfma_f32_16x16x32_bf16 v[2:5], v[178:181], v[210:213], v[2:5]
	v_mfma_f32_16x16x32_bf16 v[54:57], v[174:177], v[190:193], v[54:57]
	v_mfma_f32_16x16x32_bf16 v[50:53], v[182:185], v[190:193], v[50:53]
	v_mfma_f32_16x16x32_bf16 v[38:41], v[174:177], v[198:201], v[38:41]
	v_mfma_f32_16x16x32_bf16 v[34:37], v[182:185], v[198:201], v[34:37]
	v_mfma_f32_16x16x32_bf16 v[22:25], v[174:177], v[206:209], v[22:25]
	v_mfma_f32_16x16x32_bf16 v[18:21], v[182:185], v[206:209], v[18:21]
	v_mfma_f32_16x16x32_bf16 v[6:9], v[174:177], v[214:217], v[6:9]
	v_mfma_f32_16x16x32_bf16 v[2:5], v[182:185], v[214:217], v[2:5]
	s_setprio 0
	s_barrier
	v_add_u32_e32 v154, s47, v164
	v_add_u32_e32 v182, s72, v164
	ds_read_b128 v[142:145], v154
	ds_read_b128 v[146:149], v154 offset:1024
	ds_read_b128 v[150:153], v154 offset:2048
	ds_read_b128 v[154:157], v154 offset:3072
	ds_read_b128 v[158:161], v182
	ds_read_b128 v[174:177], v182 offset:1024
	ds_read_b128 v[178:181], v182 offset:2048
	ds_read_b128 v[182:185], v182 offset:3072
	s_add_u32 s70, s70, 0x80000
	s_addc_u32 s71, s71, 0
	v_lshl_add_u64 v[224:225], s[70:71], 0, v[130:131]
	ds_read_b128 v[186:189], v173 offset:32768
	ds_read_b128 v[190:193], v173 offset:33792
	ds_read_b128 v[194:197], v173 offset:34816
	ds_read_b128 v[198:201], v173 offset:35840
	ds_read_b128 v[202:205], v173 offset:36864
	ds_read_b128 v[206:209], v173 offset:37888
	ds_read_b128 v[210:213], v173 offset:38912
	ds_read_b128 v[214:217], v173 offset:39936
	s_mov_b32 m0, s51
	s_nop 0
	global_load_lds_dwordx4 v[220:221], off
	s_mov_b32 m0, s52
	s_nop 0
	global_load_lds_dwordx4 v[222:223], off
	s_mov_b32 m0, s53
	s_nop 0
	global_load_lds_dwordx4 v[224:225], off
	v_lshl_add_u64 v[224:225], s[70:71], 0, v[132:133]
	s_mov_b32 m0, s56
	s_nop 0
	global_load_lds_dwordx4 v[224:225], off
	s_waitcnt vmcnt(8)
	s_waitcnt lgkmcnt(0)
	s_barrier
	s_setprio 1
	s_waitcnt lgkmcnt(0)
	v_mfma_f32_16x16x32_bf16 v[126:129], v[142:145], v[186:189], v[126:129]
	v_mfma_f32_16x16x32_bf16 v[122:125], v[150:153], v[186:189], v[122:125]
	v_mfma_f32_16x16x32_bf16 v[110:113], v[142:145], v[194:197], v[110:113]
	v_mfma_f32_16x16x32_bf16 v[106:109], v[150:153], v[194:197], v[106:109]
	v_mfma_f32_16x16x32_bf16 v[94:97], v[142:145], v[202:205], v[94:97]
	v_mfma_f32_16x16x32_bf16 v[90:93], v[150:153], v[202:205], v[90:93]
	v_mfma_f32_16x16x32_bf16 v[78:81], v[142:145], v[210:213], v[78:81]
	v_mfma_f32_16x16x32_bf16 v[74:77], v[150:153], v[210:213], v[74:77]
	v_mfma_f32_16x16x32_bf16 v[126:129], v[146:149], v[190:193], v[126:129]
	v_mfma_f32_16x16x32_bf16 v[122:125], v[154:157], v[190:193], v[122:125]
	v_mfma_f32_16x16x32_bf16 v[110:113], v[146:149], v[198:201], v[110:113]
	v_mfma_f32_16x16x32_bf16 v[106:109], v[154:157], v[198:201], v[106:109]
	v_mfma_f32_16x16x32_bf16 v[94:97], v[146:149], v[206:209], v[94:97]
	v_mfma_f32_16x16x32_bf16 v[90:93], v[154:157], v[206:209], v[90:93]
	v_mfma_f32_16x16x32_bf16 v[78:81], v[146:149], v[214:217], v[78:81]
	v_mfma_f32_16x16x32_bf16 v[74:77], v[154:157], v[214:217], v[74:77]
	s_setprio 0
	s_setprio 1
	v_mfma_f32_16x16x32_bf16 v[118:121], v[158:161], v[186:189], v[118:121]
	v_mfma_f32_16x16x32_bf16 v[114:117], v[178:181], v[186:189], v[114:117]
	v_mfma_f32_16x16x32_bf16 v[102:105], v[158:161], v[194:197], v[102:105]
	v_mfma_f32_16x16x32_bf16 v[98:101], v[178:181], v[194:197], v[98:101]
	v_mfma_f32_16x16x32_bf16 v[86:89], v[158:161], v[202:205], v[86:89]
	v_mfma_f32_16x16x32_bf16 v[82:85], v[178:181], v[202:205], v[82:85]
	v_mfma_f32_16x16x32_bf16 v[70:73], v[158:161], v[210:213], v[70:73]
	v_mfma_f32_16x16x32_bf16 v[66:69], v[178:181], v[210:213], v[66:69]
	v_mfma_f32_16x16x32_bf16 v[118:121], v[174:177], v[190:193], v[118:121]
	v_mfma_f32_16x16x32_bf16 v[114:117], v[182:185], v[190:193], v[114:117]
	v_mfma_f32_16x16x32_bf16 v[102:105], v[174:177], v[198:201], v[102:105]
	v_mfma_f32_16x16x32_bf16 v[98:101], v[182:185], v[198:201], v[98:101]
	v_mfma_f32_16x16x32_bf16 v[86:89], v[174:177], v[206:209], v[86:89]
	v_mfma_f32_16x16x32_bf16 v[82:85], v[182:185], v[206:209], v[82:85]
	v_mfma_f32_16x16x32_bf16 v[70:73], v[174:177], v[214:217], v[70:73]
	v_mfma_f32_16x16x32_bf16 v[66:69], v[182:185], v[214:217], v[66:69]
	s_setprio 0
	s_barrier
	s_add_i32 s70, s47, s49
	v_lshl_add_u64 v[162:163], v[162:163], 0, s[40:41]
	s_mov_b32 m0, s70
	ds_read_b128 v[186:189], v173 offset:49152
	ds_read_b128 v[190:193], v173 offset:50176
	ds_read_b128 v[194:197], v173 offset:51200
	ds_read_b128 v[198:201], v173 offset:52224
	ds_read_b128 v[202:205], v173 offset:53248
	ds_read_b128 v[206:209], v173 offset:54272
	ds_read_b128 v[210:213], v173 offset:55296
	ds_read_b128 v[214:217], v173 offset:56320
	global_load_lds_dwordx4 v[162:163], off
	s_add_i32 m0, s70, 0x2000
	s_add_u32 s68, s68, 0x80080
	v_lshl_add_u64 v[162:163], v[218:219], 0, s[40:41]
	s_addc_u32 s69, s69, 0
	s_add_i32 s70, s72, s49
	global_load_lds_dwordx4 v[162:163], off
	v_lshl_add_u64 v[162:163], s[68:69], 0, v[130:131]
	s_mov_b32 m0, s70
	s_nop 0
	global_load_lds_dwordx4 v[162:163], off
	v_lshl_add_u64 v[162:163], s[68:69], 0, v[132:133]
	s_add_i32 m0, s70, 0x2000
	s_nop 0
	global_load_lds_dwordx4 v[162:163], off
	s_waitcnt vmcnt(6)
	s_waitcnt lgkmcnt(0)
	s_barrier
	s_setprio 1
	s_waitcnt lgkmcnt(0)
	v_mfma_f32_16x16x32_bf16 v[62:65], v[142:145], v[186:189], v[62:65]
	v_mfma_f32_16x16x32_bf16 v[58:61], v[150:153], v[186:189], v[58:61]
	v_mfma_f32_16x16x32_bf16 v[46:49], v[142:145], v[194:197], v[46:49]
	v_mfma_f32_16x16x32_bf16 v[42:45], v[150:153], v[194:197], v[42:45]
	v_mfma_f32_16x16x32_bf16 v[30:33], v[142:145], v[202:205], v[30:33]
	v_mfma_f32_16x16x32_bf16 v[26:29], v[150:153], v[202:205], v[26:29]
	v_mfma_f32_16x16x32_bf16 v[14:17], v[142:145], v[210:213], v[14:17]
	v_mfma_f32_16x16x32_bf16 v[10:13], v[150:153], v[210:213], v[10:13]
	v_mfma_f32_16x16x32_bf16 v[62:65], v[146:149], v[190:193], v[62:65]
	v_mfma_f32_16x16x32_bf16 v[58:61], v[154:157], v[190:193], v[58:61]
	v_mfma_f32_16x16x32_bf16 v[46:49], v[146:149], v[198:201], v[46:49]
	v_mfma_f32_16x16x32_bf16 v[42:45], v[154:157], v[198:201], v[42:45]
	v_mfma_f32_16x16x32_bf16 v[30:33], v[146:149], v[206:209], v[30:33]
	v_mfma_f32_16x16x32_bf16 v[26:29], v[154:157], v[206:209], v[26:29]
	v_mfma_f32_16x16x32_bf16 v[14:17], v[146:149], v[214:217], v[14:17]
	v_mfma_f32_16x16x32_bf16 v[10:13], v[154:157], v[214:217], v[10:13]
	s_setprio 0
	s_setprio 1
	v_mfma_f32_16x16x32_bf16 v[54:57], v[158:161], v[186:189], v[54:57]
	v_mfma_f32_16x16x32_bf16 v[50:53], v[178:181], v[186:189], v[50:53]
	v_mfma_f32_16x16x32_bf16 v[38:41], v[158:161], v[194:197], v[38:41]
	v_mfma_f32_16x16x32_bf16 v[34:37], v[178:181], v[194:197], v[34:37]
	v_mfma_f32_16x16x32_bf16 v[22:25], v[158:161], v[202:205], v[22:25]
	v_mfma_f32_16x16x32_bf16 v[18:21], v[178:181], v[202:205], v[18:21]
	v_mfma_f32_16x16x32_bf16 v[6:9], v[158:161], v[210:213], v[6:9]
	v_mfma_f32_16x16x32_bf16 v[2:5], v[178:181], v[210:213], v[2:5]
	v_mfma_f32_16x16x32_bf16 v[54:57], v[174:177], v[190:193], v[54:57]
	v_mfma_f32_16x16x32_bf16 v[50:53], v[182:185], v[190:193], v[50:53]
	v_mfma_f32_16x16x32_bf16 v[38:41], v[174:177], v[198:201], v[38:41]
	v_mfma_f32_16x16x32_bf16 v[34:37], v[182:185], v[198:201], v[34:37]
	v_mfma_f32_16x16x32_bf16 v[22:25], v[174:177], v[206:209], v[22:25]
	v_mfma_f32_16x16x32_bf16 v[18:21], v[182:185], v[206:209], v[18:21]
	v_mfma_f32_16x16x32_bf16 v[6:9], v[174:177], v[214:217], v[6:9]
	v_mfma_f32_16x16x32_bf16 v[2:5], v[182:185], v[214:217], v[2:5]
	s_setprio 0
	s_barrier
	s_add_i32 s81, s81, 2
	s_add_u32 s79, s79, 0x100
	s_addc_u32 s80, s80, 0
	s_add_u32 s10, s10, 0x100
	s_addc_u32 s11, s11, 0
	s_cmp_gt_u32 s81, 29
	s_cbranch_scc0 .LBB0_848
	s_and_b64 vcc, exec, s[42:43]
	s_cbranch_vccz .LBB0_851
	s_barrier

.LBB0_2756:
	s_add_u32 s100, s60, 0xfff80000
	s_addc_u32 s101, s61, -1
	v_lshl_add_u64 v[228:229], s[100:101], 0, v[130:131]
	v_lshl_add_u64 v[230:231], s[100:101], 0, v[134:135]
	ds_read_b128 v[148:151], v165
	ds_read_b128 v[152:155], v165 offset:1024
	ds_read_b128 v[170:173], v165 offset:2048
	ds_read_b128 v[174:177], v165 offset:3072
	ds_read_b128 v[178:181], v166
	ds_read_b128 v[182:185], v166 offset:1024
	ds_read_b128 v[186:189], v166 offset:2048
	ds_read_b128 v[190:193], v166 offset:3072
	s_add_u32 s62, s60, 0xfff80080
	s_addc_u32 s63, s61, -1
	s_cmp_eq_u32 s68, 28
	s_cselect_b32 s65, s41, s63
	s_cselect_b32 s64, s47, s62
	s_cselect_b32 s63, s39, s67
	s_cselect_b32 s62, s59, s66
	v_lshl_add_u64 v[156:157], s[60:61], 0, v[142:143]
	ds_read_b128 v[194:197], v167
	ds_read_b128 v[198:201], v167 offset:1024
	ds_read_b128 v[202:205], v167 offset:2048
	ds_read_b128 v[206:209], v167 offset:3072
	ds_read_b128 v[210:213], v167 offset:4096
	ds_read_b128 v[214:217], v167 offset:5120
	ds_read_b128 v[218:221], v167 offset:6144
	ds_read_b128 v[222:225], v167 offset:7168
	s_mov_b32 m0, s49
	s_nop 0
	global_load_lds_dwordx4 v[228:229], off
	s_mov_b32 m0, s51
	s_nop 0
	global_load_lds_dwordx4 v[230:231], off
	s_add_i32 m0, s1, 0xc000
	s_nop 0
	global_load_lds_dwordx4 v[156:157], off
	v_lshl_add_u64 v[156:157], s[60:61], 0, v[140:141]
	s_add_i32 m0, s1, 0xe000
	s_nop 0
	global_load_lds_dwordx4 v[156:157], off
	s_waitcnt vmcnt(8)
	s_waitcnt lgkmcnt(0)
	s_barrier
	s_setprio 1
	s_waitcnt lgkmcnt(0)
	v_mfma_f32_16x16x32_bf16 v[126:129], v[148:151], v[194:197], v[126:129]
	v_mfma_f32_16x16x32_bf16 v[122:125], v[170:173], v[194:197], v[122:125]
	v_mfma_f32_16x16x32_bf16 v[110:113], v[148:151], v[202:205], v[110:113]
	v_mfma_f32_16x16x32_bf16 v[106:109], v[170:173], v[202:205], v[106:109]
	v_mfma_f32_16x16x32_bf16 v[94:97], v[148:151], v[210:213], v[94:97]
	v_mfma_f32_16x16x32_bf16 v[90:93], v[170:173], v[210:213], v[90:93]
	v_mfma_f32_16x16x32_bf16 v[78:81], v[148:151], v[218:221], v[78:81]
	v_mfma_f32_16x16x32_bf16 v[74:77], v[170:173], v[218:221], v[74:77]
	v_mfma_f32_16x16x32_bf16 v[126:129], v[152:155], v[198:201], v[126:129]
	v_mfma_f32_16x16x32_bf16 v[122:125], v[174:177], v[198:201], v[122:125]
	v_mfma_f32_16x16x32_bf16 v[110:113], v[152:155], v[206:209], v[110:113]
	v_mfma_f32_16x16x32_bf16 v[106:109], v[174:177], v[206:209], v[106:109]
	v_mfma_f32_16x16x32_bf16 v[94:97], v[152:155], v[214:217], v[94:97]
	v_mfma_f32_16x16x32_bf16 v[90:93], v[174:177], v[214:217], v[90:93]
	v_mfma_f32_16x16x32_bf16 v[78:81], v[152:155], v[222:225], v[78:81]
	v_mfma_f32_16x16x32_bf16 v[74:77], v[174:177], v[222:225], v[74:77]
	s_setprio 0
	s_setprio 1
	v_mfma_f32_16x16x32_bf16 v[118:121], v[178:181], v[194:197], v[118:121]
	v_mfma_f32_16x16x32_bf16 v[114:117], v[186:189], v[194:197], v[114:117]
	v_mfma_f32_16x16x32_bf16 v[102:105], v[178:181], v[202:205], v[102:105]
	v_mfma_f32_16x16x32_bf16 v[98:101], v[186:189], v[202:205], v[98:101]
	v_mfma_f32_16x16x32_bf16 v[86:89], v[178:181], v[210:213], v[86:89]
	v_mfma_f32_16x16x32_bf16 v[82:85], v[186:189], v[210:213], v[82:85]
	v_mfma_f32_16x16x32_bf16 v[70:73], v[178:181], v[218:221], v[70:73]
	v_mfma_f32_16x16x32_bf16 v[66:69], v[186:189], v[218:221], v[66:69]
	v_mfma_f32_16x16x32_bf16 v[118:121], v[182:185], v[198:201], v[118:121]
	v_mfma_f32_16x16x32_bf16 v[114:117], v[190:193], v[198:201], v[114:117]
	v_mfma_f32_16x16x32_bf16 v[102:105], v[182:185], v[206:209], v[102:105]
	v_mfma_f32_16x16x32_bf16 v[98:101], v[190:193], v[206:209], v[98:101]
	v_mfma_f32_16x16x32_bf16 v[86:89], v[182:185], v[214:217], v[86:89]
	v_mfma_f32_16x16x32_bf16 v[82:85], v[190:193], v[214:217], v[82:85]
	v_mfma_f32_16x16x32_bf16 v[70:73], v[182:185], v[222:225], v[70:73]
	v_mfma_f32_16x16x32_bf16 v[66:69], v[190:193], v[222:225], v[66:69]
	s_setprio 0
	s_barrier
	s_add_i32 s69, s56, s0
	v_lshl_add_u64 v[156:157], s[62:63], 0, v[132:133]
	s_mov_b32 m0, s69
	ds_read_b128 v[194:197], v167 offset:16384
	ds_read_b128 v[198:201], v167 offset:17408
	ds_read_b128 v[202:205], v167 offset:18432
	ds_read_b128 v[206:209], v167 offset:19456
	ds_read_b128 v[210:213], v167 offset:20480
	ds_read_b128 v[214:217], v167 offset:21504
	ds_read_b128 v[218:221], v167 offset:22528
	ds_read_b128 v[222:225], v167 offset:23552
	global_load_lds_dwordx4 v[156:157], off
	s_add_i32 m0, s69, 0x2000
	s_add_u32 s70, s62, 0x80000
	v_lshl_add_u64 v[226:227], s[62:63], 0, v[136:137]
	s_addc_u32 s71, s63, 0
	s_add_i32 s69, s57, s0
	global_load_lds_dwordx4 v[226:227], off
	v_lshl_add_u64 v[228:229], s[70:71], 0, v[132:133]
	s_mov_b32 m0, s69
	v_lshl_add_u64 v[230:231], s[64:65], 0, v[134:135]
	global_load_lds_dwordx4 v[228:229], off
	v_lshl_add_u64 v[228:229], s[70:71], 0, v[136:137]
	s_add_i32 m0, s69, 0x2000
	s_nop 0
	global_load_lds_dwordx4 v[228:229], off
	v_lshl_add_u64 v[228:229], s[64:65], 0, v[130:131]
	s_waitcnt vmcnt(6)
	s_waitcnt lgkmcnt(0)
	s_barrier
	s_setprio 1
	s_waitcnt lgkmcnt(0)
	v_mfma_f32_16x16x32_bf16 v[62:65], v[148:151], v[194:197], v[62:65]
	v_mfma_f32_16x16x32_bf16 v[58:61], v[170:173], v[194:197], v[58:61]
	v_mfma_f32_16x16x32_bf16 v[46:49], v[148:151], v[202:205], v[46:49]
	v_mfma_f32_16x16x32_bf16 v[42:45], v[170:173], v[202:205], v[42:45]
	v_mfma_f32_16x16x32_bf16 v[30:33], v[148:151], v[210:213], v[30:33]
	v_mfma_f32_16x16x32_bf16 v[26:29], v[170:173], v[210:213], v[26:29]
	v_mfma_f32_16x16x32_bf16 v[14:17], v[148:151], v[218:221], v[14:17]
	v_mfma_f32_16x16x32_bf16 v[10:13], v[170:173], v[218:221], v[10:13]
	v_mfma_f32_16x16x32_bf16 v[62:65], v[152:155], v[198:201], v[62:65]
	v_mfma_f32_16x16x32_bf16 v[58:61], v[174:177], v[198:201], v[58:61]
	v_mfma_f32_16x16x32_bf16 v[46:49], v[152:155], v[206:209], v[46:49]
	v_mfma_f32_16x16x32_bf16 v[42:45], v[174:177], v[206:209], v[42:45]
	v_mfma_f32_16x16x32_bf16 v[30:33], v[152:155], v[214:217], v[30:33]
	v_mfma_f32_16x16x32_bf16 v[26:29], v[174:177], v[214:217], v[26:29]
	v_mfma_f32_16x16x32_bf16 v[14:17], v[152:155], v[222:225], v[14:17]
	v_mfma_f32_16x16x32_bf16 v[10:13], v[174:177], v[222:225], v[10:13]
	s_setprio 0
	s_setprio 1
	v_mfma_f32_16x16x32_bf16 v[54:57], v[178:181], v[194:197], v[54:57]
	v_mfma_f32_16x16x32_bf16 v[50:53], v[186:189], v[194:197], v[50:53]
	v_mfma_f32_16x16x32_bf16 v[38:41], v[178:181], v[202:205], v[38:41]
	v_mfma_f32_16x16x32_bf16 v[34:37], v[186:189], v[202:205], v[34:37]
	v_mfma_f32_16x16x32_bf16 v[22:25], v[178:181], v[210:213], v[22:25]
	v_mfma_f32_16x16x32_bf16 v[18:21], v[186:189], v[210:213], v[18:21]
	v_mfma_f32_16x16x32_bf16 v[6:9], v[178:181], v[218:221], v[6:9]
	v_mfma_f32_16x16x32_bf16 v[2:5], v[186:189], v[218:221], v[2:5]
	v_mfma_f32_16x16x32_bf16 v[54:57], v[182:185], v[198:201], v[54:57]
	v_mfma_f32_16x16x32_bf16 v[50:53], v[190:193], v[198:201], v[50:53]
	v_mfma_f32_16x16x32_bf16 v[38:41], v[182:185], v[206:209], v[38:41]
	v_mfma_f32_16x16x32_bf16 v[34:37], v[190:193], v[206:209], v[34:37]
	v_mfma_f32_16x16x32_bf16 v[22:25], v[182:185], v[214:217], v[22:25]
	v_mfma_f32_16x16x32_bf16 v[18:21], v[190:193], v[214:217], v[18:21]
	v_mfma_f32_16x16x32_bf16 v[6:9], v[182:185], v[222:225], v[6:9]
	v_mfma_f32_16x16x32_bf16 v[2:5], v[190:193], v[222:225], v[2:5]
	s_setprio 0
	s_barrier
	s_add_i32 s69, 0, 0x18000
	v_add_u32_e32 v169, s69, v160
	s_add_i32 s70, 0, 0x1c000
	ds_read_b128 v[148:151], v169
	ds_read_b128 v[152:155], v169 offset:1024
	ds_read_b128 v[170:173], v169 offset:2048
	ds_read_b128 v[174:177], v169 offset:3072
	v_add_u32_e32 v169, s70, v160
	ds_read_b128 v[178:181], v169
	ds_read_b128 v[182:185], v169 offset:1024
	ds_read_b128 v[186:189], v169 offset:2048
	ds_read_b128 v[190:193], v169 offset:3072
	s_add_u32 s64, s64, 0x80000
	s_addc_u32 s65, s65, 0
	v_lshl_add_u64 v[232:233], s[64:65], 0, v[130:131]
	ds_read_b128 v[194:197], v167 offset:32768
	ds_read_b128 v[198:201], v167 offset:33792
	ds_read_b128 v[202:205], v167 offset:34816
	ds_read_b128 v[206:209], v167 offset:35840
	ds_read_b128 v[210:213], v167 offset:36864
	ds_read_b128 v[214:217], v167 offset:37888
	ds_read_b128 v[218:221], v167 offset:38912
	ds_read_b128 v[222:225], v167 offset:39936
	s_mov_b32 m0, s1
	s_nop 0
	global_load_lds_dwordx4 v[228:229], off
	s_mov_b32 m0, s33
	s_nop 0
	global_load_lds_dwordx4 v[230:231], off
	s_mov_b32 m0, s35
	s_nop 0
	global_load_lds_dwordx4 v[232:233], off
	v_lshl_add_u64 v[232:233], s[64:65], 0, v[134:135]
	s_mov_b32 m0, s37
	s_nop 0
	global_load_lds_dwordx4 v[232:233], off
	s_waitcnt vmcnt(8)
	s_waitcnt lgkmcnt(0)
	s_barrier
	s_setprio 1
	s_waitcnt lgkmcnt(0)
	v_mfma_f32_16x16x32_bf16 v[126:129], v[148:151], v[194:197], v[126:129]
	v_mfma_f32_16x16x32_bf16 v[122:125], v[170:173], v[194:197], v[122:125]
	v_mfma_f32_16x16x32_bf16 v[110:113], v[148:151], v[202:205], v[110:113]
	v_mfma_f32_16x16x32_bf16 v[106:109], v[170:173], v[202:205], v[106:109]
	v_mfma_f32_16x16x32_bf16 v[94:97], v[148:151], v[210:213], v[94:97]
	v_mfma_f32_16x16x32_bf16 v[90:93], v[170:173], v[210:213], v[90:93]
	v_mfma_f32_16x16x32_bf16 v[78:81], v[148:151], v[218:221], v[78:81]
	v_mfma_f32_16x16x32_bf16 v[74:77], v[170:173], v[218:221], v[74:77]
	v_mfma_f32_16x16x32_bf16 v[126:129], v[152:155], v[198:201], v[126:129]
	v_mfma_f32_16x16x32_bf16 v[122:125], v[174:177], v[198:201], v[122:125]
	v_mfma_f32_16x16x32_bf16 v[110:113], v[152:155], v[206:209], v[110:113]
	v_mfma_f32_16x16x32_bf16 v[106:109], v[174:177], v[206:209], v[106:109]
	v_mfma_f32_16x16x32_bf16 v[94:97], v[152:155], v[214:217], v[94:97]
	v_mfma_f32_16x16x32_bf16 v[90:93], v[174:177], v[214:217], v[90:93]
	v_mfma_f32_16x16x32_bf16 v[78:81], v[152:155], v[222:225], v[78:81]
	v_mfma_f32_16x16x32_bf16 v[74:77], v[174:177], v[222:225], v[74:77]
	s_setprio 0
	s_setprio 1
	v_mfma_f32_16x16x32_bf16 v[118:121], v[178:181], v[194:197], v[118:121]
	v_mfma_f32_16x16x32_bf16 v[114:117], v[186:189], v[194:197], v[114:117]
	v_mfma_f32_16x16x32_bf16 v[102:105], v[178:181], v[202:205], v[102:105]
	v_mfma_f32_16x16x32_bf16 v[98:101], v[186:189], v[202:205], v[98:101]
	v_mfma_f32_16x16x32_bf16 v[86:89], v[178:181], v[210:213], v[86:89]
	v_mfma_f32_16x16x32_bf16 v[82:85], v[186:189], v[210:213], v[82:85]
	v_mfma_f32_16x16x32_bf16 v[70:73], v[178:181], v[218:221], v[70:73]
	v_mfma_f32_16x16x32_bf16 v[66:69], v[186:189], v[218:221], v[66:69]
	v_mfma_f32_16x16x32_bf16 v[118:121], v[182:185], v[198:201], v[118:121]
	v_mfma_f32_16x16x32_bf16 v[114:117], v[190:193], v[198:201], v[114:117]
	v_mfma_f32_16x16x32_bf16 v[102:105], v[182:185], v[206:209], v[102:105]
	v_mfma_f32_16x16x32_bf16 v[98:101], v[190:193], v[206:209], v[98:101]
	v_mfma_f32_16x16x32_bf16 v[86:89], v[182:185], v[214:217], v[86:89]
	v_mfma_f32_16x16x32_bf16 v[82:85], v[190:193], v[214:217], v[82:85]
	v_mfma_f32_16x16x32_bf16 v[70:73], v[182:185], v[222:225], v[70:73]
	v_mfma_f32_16x16x32_bf16 v[66:69], v[190:193], v[222:225], v[66:69]
	s_setprio 0
	s_barrier
	s_add_i32 s64, s69, s0
	v_lshl_add_u64 v[156:157], v[156:157], 0, s[28:29]
	s_mov_b32 m0, s64
	ds_read_b128 v[194:197], v167 offset:49152
	ds_read_b128 v[198:201], v167 offset:50176
	ds_read_b128 v[202:205], v167 offset:51200
	ds_read_b128 v[206:209], v167 offset:52224
	ds_read_b128 v[210:213], v167 offset:53248
	ds_read_b128 v[214:217], v167 offset:54272
	ds_read_b128 v[218:221], v167 offset:55296
	ds_read_b128 v[222:225], v167 offset:56320
	global_load_lds_dwordx4 v[156:157], off
	s_add_i32 m0, s64, 0x2000
	s_add_u32 s62, s62, 0x80080
	v_lshl_add_u64 v[156:157], v[226:227], 0, s[28:29]
	s_addc_u32 s63, s63, 0
	s_add_i32 s64, s70, s0
	global_load_lds_dwordx4 v[156:157], off
	v_lshl_add_u64 v[156:157], s[62:63], 0, v[132:133]
	s_mov_b32 m0, s64
	s_nop 0
	global_load_lds_dwordx4 v[156:157], off
	v_lshl_add_u64 v[156:157], s[62:63], 0, v[136:137]
	s_add_i32 m0, s64, 0x2000
	s_nop 0
	global_load_lds_dwordx4 v[156:157], off
	s_waitcnt vmcnt(6)
	s_waitcnt lgkmcnt(0)
	s_barrier
	s_setprio 1
	s_waitcnt lgkmcnt(0)
	v_mfma_f32_16x16x32_bf16 v[62:65], v[148:151], v[194:197], v[62:65]
	v_mfma_f32_16x16x32_bf16 v[58:61], v[170:173], v[194:197], v[58:61]
	v_mfma_f32_16x16x32_bf16 v[46:49], v[148:151], v[202:205], v[46:49]
	v_mfma_f32_16x16x32_bf16 v[42:45], v[170:173], v[202:205], v[42:45]
	v_mfma_f32_16x16x32_bf16 v[30:33], v[148:151], v[210:213], v[30:33]
	v_mfma_f32_16x16x32_bf16 v[26:29], v[170:173], v[210:213], v[26:29]
	v_mfma_f32_16x16x32_bf16 v[14:17], v[148:151], v[218:221], v[14:17]
	v_mfma_f32_16x16x32_bf16 v[10:13], v[170:173], v[218:221], v[10:13]
	v_mfma_f32_16x16x32_bf16 v[62:65], v[152:155], v[198:201], v[62:65]
	v_mfma_f32_16x16x32_bf16 v[58:61], v[174:177], v[198:201], v[58:61]
	v_mfma_f32_16x16x32_bf16 v[46:49], v[152:155], v[206:209], v[46:49]
	v_mfma_f32_16x16x32_bf16 v[42:45], v[174:177], v[206:209], v[42:45]
	v_mfma_f32_16x16x32_bf16 v[30:33], v[152:155], v[214:217], v[30:33]
	v_mfma_f32_16x16x32_bf16 v[26:29], v[174:177], v[214:217], v[26:29]
	v_mfma_f32_16x16x32_bf16 v[14:17], v[152:155], v[222:225], v[14:17]
	v_mfma_f32_16x16x32_bf16 v[10:13], v[174:177], v[222:225], v[10:13]
	s_setprio 0
	s_setprio 1
	v_mfma_f32_16x16x32_bf16 v[54:57], v[178:181], v[194:197], v[54:57]
	v_mfma_f32_16x16x32_bf16 v[50:53], v[186:189], v[194:197], v[50:53]
	v_mfma_f32_16x16x32_bf16 v[38:41], v[178:181], v[202:205], v[38:41]
	v_mfma_f32_16x16x32_bf16 v[34:37], v[186:189], v[202:205], v[34:37]
	v_mfma_f32_16x16x32_bf16 v[22:25], v[178:181], v[210:213], v[22:25]
	v_mfma_f32_16x16x32_bf16 v[18:21], v[186:189], v[210:213], v[18:21]
	v_mfma_f32_16x16x32_bf16 v[6:9], v[178:181], v[218:221], v[6:9]
	v_mfma_f32_16x16x32_bf16 v[2:5], v[186:189], v[218:221], v[2:5]
	v_mfma_f32_16x16x32_bf16 v[54:57], v[182:185], v[198:201], v[54:57]
	v_mfma_f32_16x16x32_bf16 v[50:53], v[190:193], v[198:201], v[50:53]
	v_mfma_f32_16x16x32_bf16 v[38:41], v[182:185], v[206:209], v[38:41]
	v_mfma_f32_16x16x32_bf16 v[34:37], v[190:193], v[206:209], v[34:37]
	v_mfma_f32_16x16x32_bf16 v[22:25], v[182:185], v[214:217], v[22:25]
	v_mfma_f32_16x16x32_bf16 v[18:21], v[190:193], v[214:217], v[18:21]
	v_mfma_f32_16x16x32_bf16 v[6:9], v[182:185], v[222:225], v[6:9]
	v_mfma_f32_16x16x32_bf16 v[2:5], v[190:193], v[222:225], v[2:5]
	s_setprio 0
	s_barrier
	s_add_i32 s68, s68, 2
	s_add_u32 s66, s66, 0x100
	s_addc_u32 s67, s67, 0
	s_add_u32 s60, s60, 0x100
	s_addc_u32 s61, s61, 0
	s_cmp_gt_u32 s68, 29
	s_cbranch_scc0 .LBB0_2756
	s_and_b64 vcc, exec, s[30:31]
	s_cbranch_vccz .LBB0_2759
	s_barrier

.LBB0_2869:
	s_add_u32 s100, s46, 0xfff80000
	s_addc_u32 s101, s47, -1
	v_lshl_add_u64 v[234:235], s[100:101], 0, v[152:153]
	v_lshl_add_u64 v[236:237], s[100:101], 0, v[148:149]
	ds_read_b128 v[130:133], v198
	ds_read_b128 v[134:137], v198 offset:1024
	ds_read_b128 v[138:141], v198 offset:2048
	ds_read_b128 v[142:145], v198 offset:3072
	ds_read_b128 v[158:161], v199
	ds_read_b128 v[162:165], v199 offset:1024
	ds_read_b128 v[166:169], v199 offset:2048
	ds_read_b128 v[180:183], v199 offset:3072
	s_add_u32 s58, s46, 0xfff80080
	s_addc_u32 s59, s47, -1
	s_cmp_eq_u32 s73, 28
	s_cselect_b32 s61, s35, s59
	s_cselect_b32 s60, s69, s58
	s_cselect_b32 s59, s37, s72
	s_cselect_b32 s58, s70, s71
	v_lshl_add_u64 v[172:173], s[46:47], 0, v[156:157]
	ds_read_b128 v[186:189], v200
	ds_read_b128 v[190:193], v200 offset:1024
	ds_read_b128 v[194:197], v200 offset:2048
	ds_read_b128 v[214:217], v200 offset:3072
	ds_read_b128 v[218:221], v200 offset:4096
	ds_read_b128 v[222:225], v200 offset:5120
	ds_read_b128 v[226:229], v200 offset:6144
	ds_read_b128 v[230:233], v200 offset:7168
	s_mov_b32 m0, s66
	s_nop 0
	global_load_lds_dwordx4 v[234:235], off
	s_mov_b32 m0, s67
	s_nop 0
	global_load_lds_dwordx4 v[236:237], off
	s_add_i32 m0, s45, 0xc000
	s_nop 0
	global_load_lds_dwordx4 v[172:173], off
	v_lshl_add_u64 v[172:173], s[46:47], 0, v[154:155]
	s_add_i32 m0, s45, 0xe000
	s_nop 0
	global_load_lds_dwordx4 v[172:173], off
	s_waitcnt vmcnt(8)
	s_waitcnt lgkmcnt(0)
	s_barrier
	s_setprio 1
	s_waitcnt lgkmcnt(0)
	v_mfma_f32_16x16x32_bf16 v[126:129], v[130:133], v[186:189], v[126:129]
	v_mfma_f32_16x16x32_bf16 v[122:125], v[138:141], v[186:189], v[122:125]
	v_mfma_f32_16x16x32_bf16 v[118:121], v[130:133], v[194:197], v[118:121]
	v_mfma_f32_16x16x32_bf16 v[114:117], v[138:141], v[194:197], v[114:117]
	v_mfma_f32_16x16x32_bf16 v[110:113], v[130:133], v[218:221], v[110:113]
	v_mfma_f32_16x16x32_bf16 v[106:109], v[138:141], v[218:221], v[106:109]
	v_mfma_f32_16x16x32_bf16 v[102:105], v[130:133], v[226:229], v[102:105]
	v_mfma_f32_16x16x32_bf16 v[98:101], v[138:141], v[226:229], v[98:101]
	v_mfma_f32_16x16x32_bf16 v[126:129], v[134:137], v[190:193], v[126:129]
	v_mfma_f32_16x16x32_bf16 v[122:125], v[142:145], v[190:193], v[122:125]
	v_mfma_f32_16x16x32_bf16 v[118:121], v[134:137], v[214:217], v[118:121]
	v_mfma_f32_16x16x32_bf16 v[114:117], v[142:145], v[214:217], v[114:117]
	v_mfma_f32_16x16x32_bf16 v[110:113], v[134:137], v[222:225], v[110:113]
	v_mfma_f32_16x16x32_bf16 v[106:109], v[142:145], v[222:225], v[106:109]
	v_mfma_f32_16x16x32_bf16 v[102:105], v[134:137], v[230:233], v[102:105]
	v_mfma_f32_16x16x32_bf16 v[98:101], v[142:145], v[230:233], v[98:101]
	s_setprio 0
	s_setprio 1
	v_mfma_f32_16x16x32_bf16 v[70:73], v[158:161], v[186:189], v[70:73]
	v_mfma_f32_16x16x32_bf16 v[58:61], v[166:169], v[186:189], v[58:61]
	v_mfma_f32_16x16x32_bf16 v[54:57], v[158:161], v[194:197], v[54:57]
	v_mfma_f32_16x16x32_bf16 v[50:53], v[166:169], v[194:197], v[50:53]
	v_mfma_f32_16x16x32_bf16 v[46:49], v[158:161], v[218:221], v[46:49]
	v_mfma_f32_16x16x32_bf16 v[42:45], v[166:169], v[218:221], v[42:45]
	v_mfma_f32_16x16x32_bf16 v[38:41], v[158:161], v[226:229], v[38:41]
	v_mfma_f32_16x16x32_bf16 v[34:37], v[166:169], v[226:229], v[34:37]
	v_mfma_f32_16x16x32_bf16 v[70:73], v[162:165], v[190:193], v[70:73]
	v_mfma_f32_16x16x32_bf16 v[58:61], v[180:183], v[190:193], v[58:61]
	v_mfma_f32_16x16x32_bf16 v[54:57], v[162:165], v[214:217], v[54:57]
	v_mfma_f32_16x16x32_bf16 v[50:53], v[180:183], v[214:217], v[50:53]
	v_mfma_f32_16x16x32_bf16 v[46:49], v[162:165], v[222:225], v[46:49]
	v_mfma_f32_16x16x32_bf16 v[42:45], v[180:183], v[222:225], v[42:45]
	v_mfma_f32_16x16x32_bf16 v[38:41], v[162:165], v[230:233], v[38:41]
	v_mfma_f32_16x16x32_bf16 v[34:37], v[180:183], v[230:233], v[34:37]
	s_setprio 0
	s_barrier
	s_add_i32 s74, s0, s62
	v_lshl_add_u64 v[172:173], s[58:59], 0, v[150:151]
	s_mov_b32 m0, s74
	ds_read_b128 v[186:189], v200 offset:16384
	ds_read_b128 v[190:193], v200 offset:17408
	ds_read_b128 v[194:197], v200 offset:18432
	ds_read_b128 v[214:217], v200 offset:19456
	ds_read_b128 v[218:221], v200 offset:20480
	ds_read_b128 v[222:225], v200 offset:21504
	ds_read_b128 v[226:229], v200 offset:22528
	ds_read_b128 v[230:233], v200 offset:23552
	global_load_lds_dwordx4 v[172:173], off
	s_add_i32 m0, s74, 0x2000
	s_add_u32 s74, s58, 0x80000
	v_lshl_add_u64 v[176:177], s[58:59], 0, v[146:147]
	s_addc_u32 s75, s59, 0
	s_add_i32 s76, s1, s62
	global_load_lds_dwordx4 v[176:177], off
	v_lshl_add_u64 v[234:235], s[74:75], 0, v[150:151]
	s_mov_b32 m0, s76
	v_lshl_add_u64 v[236:237], s[60:61], 0, v[148:149]
	global_load_lds_dwordx4 v[234:235], off
	v_lshl_add_u64 v[234:235], s[74:75], 0, v[146:147]
	s_add_i32 m0, s76, 0x2000
	s_nop 0
	global_load_lds_dwordx4 v[234:235], off
	v_lshl_add_u64 v[234:235], s[60:61], 0, v[152:153]
	s_waitcnt vmcnt(6)
	s_waitcnt lgkmcnt(0)
	s_barrier
	s_setprio 1
	s_waitcnt lgkmcnt(0)
	v_mfma_f32_16x16x32_bf16 v[94:97], v[130:133], v[186:189], v[94:97]
	v_mfma_f32_16x16x32_bf16 v[90:93], v[138:141], v[186:189], v[90:93]
	v_mfma_f32_16x16x32_bf16 v[86:89], v[130:133], v[194:197], v[86:89]
	v_mfma_f32_16x16x32_bf16 v[82:85], v[138:141], v[194:197], v[82:85]
	v_mfma_f32_16x16x32_bf16 v[78:81], v[130:133], v[218:221], v[78:81]
	v_mfma_f32_16x16x32_bf16 v[74:77], v[138:141], v[218:221], v[74:77]
	v_mfma_f32_16x16x32_bf16 v[66:69], v[130:133], v[226:229], v[66:69]
	v_mfma_f32_16x16x32_bf16 v[62:65], v[138:141], v[226:229], v[62:65]
	v_mfma_f32_16x16x32_bf16 v[94:97], v[134:137], v[190:193], v[94:97]
	v_mfma_f32_16x16x32_bf16 v[90:93], v[142:145], v[190:193], v[90:93]
	v_mfma_f32_16x16x32_bf16 v[86:89], v[134:137], v[214:217], v[86:89]
	v_mfma_f32_16x16x32_bf16 v[82:85], v[142:145], v[214:217], v[82:85]
	v_mfma_f32_16x16x32_bf16 v[78:81], v[134:137], v[222:225], v[78:81]
	v_mfma_f32_16x16x32_bf16 v[74:77], v[142:145], v[222:225], v[74:77]
	v_mfma_f32_16x16x32_bf16 v[66:69], v[134:137], v[230:233], v[66:69]
	v_mfma_f32_16x16x32_bf16 v[62:65], v[142:145], v[230:233], v[62:65]
	s_setprio 0
	s_setprio 1
	v_mfma_f32_16x16x32_bf16 v[30:33], v[158:161], v[186:189], v[30:33]
	v_mfma_f32_16x16x32_bf16 v[26:29], v[166:169], v[186:189], v[26:29]
	v_mfma_f32_16x16x32_bf16 v[22:25], v[158:161], v[194:197], v[22:25]
	v_mfma_f32_16x16x32_bf16 v[18:21], v[166:169], v[194:197], v[18:21]
	v_mfma_f32_16x16x32_bf16 v[14:17], v[158:161], v[218:221], v[14:17]
	v_mfma_f32_16x16x32_bf16 v[10:13], v[166:169], v[218:221], v[10:13]
	v_mfma_f32_16x16x32_bf16 v[6:9], v[158:161], v[226:229], v[6:9]
	v_mfma_f32_16x16x32_bf16 v[2:5], v[166:169], v[226:229], v[2:5]
	v_mfma_f32_16x16x32_bf16 v[30:33], v[162:165], v[190:193], v[30:33]
	v_mfma_f32_16x16x32_bf16 v[26:29], v[180:183], v[190:193], v[26:29]
	v_mfma_f32_16x16x32_bf16 v[22:25], v[162:165], v[214:217], v[22:25]
	v_mfma_f32_16x16x32_bf16 v[18:21], v[180:183], v[214:217], v[18:21]
	v_mfma_f32_16x16x32_bf16 v[14:17], v[162:165], v[222:225], v[14:17]
	v_mfma_f32_16x16x32_bf16 v[10:13], v[180:183], v[222:225], v[10:13]
	v_mfma_f32_16x16x32_bf16 v[6:9], v[162:165], v[230:233], v[6:9]
	v_mfma_f32_16x16x32_bf16 v[2:5], v[180:183], v[230:233], v[2:5]
	s_setprio 0
	s_barrier
	v_add_u32_e32 v142, s33, v175
	v_add_u32_e32 v170, s48, v175
	ds_read_b128 v[130:133], v142
	ds_read_b128 v[134:137], v142 offset:1024
	ds_read_b128 v[138:141], v142 offset:2048
	ds_read_b128 v[142:145], v142 offset:3072
	ds_read_b128 v[158:161], v170
	ds_read_b128 v[162:165], v170 offset:1024
	ds_read_b128 v[166:169], v170 offset:2048
	ds_read_b128 v[180:183], v170 offset:3072
	s_add_u32 s60, s60, 0x80000
	s_addc_u32 s61, s61, 0
	v_lshl_add_u64 v[238:239], s[60:61], 0, v[152:153]
	ds_read_b128 v[186:189], v200 offset:32768
	ds_read_b128 v[190:193], v200 offset:33792
	ds_read_b128 v[194:197], v200 offset:34816
	ds_read_b128 v[214:217], v200 offset:35840
	ds_read_b128 v[218:221], v200 offset:36864
	ds_read_b128 v[222:225], v200 offset:37888
	ds_read_b128 v[226:229], v200 offset:38912
	ds_read_b128 v[230:233], v200 offset:39936
	s_mov_b32 m0, s45
	s_nop 0
	global_load_lds_dwordx4 v[234:235], off
	s_mov_b32 m0, s63
	s_nop 0
	global_load_lds_dwordx4 v[236:237], off
	s_mov_b32 m0, s64
	s_nop 0
	global_load_lds_dwordx4 v[238:239], off
	v_lshl_add_u64 v[238:239], s[60:61], 0, v[148:149]
	s_mov_b32 m0, s65
	s_nop 0
	global_load_lds_dwordx4 v[238:239], off
	s_waitcnt vmcnt(8)
	s_waitcnt lgkmcnt(0)
	s_barrier
	s_setprio 1
	s_waitcnt lgkmcnt(0)
	v_mfma_f32_16x16x32_bf16 v[126:129], v[130:133], v[186:189], v[126:129]
	v_mfma_f32_16x16x32_bf16 v[122:125], v[138:141], v[186:189], v[122:125]
	v_mfma_f32_16x16x32_bf16 v[118:121], v[130:133], v[194:197], v[118:121]
	v_mfma_f32_16x16x32_bf16 v[114:117], v[138:141], v[194:197], v[114:117]
	v_mfma_f32_16x16x32_bf16 v[110:113], v[130:133], v[218:221], v[110:113]
	v_mfma_f32_16x16x32_bf16 v[106:109], v[138:141], v[218:221], v[106:109]
	v_mfma_f32_16x16x32_bf16 v[102:105], v[130:133], v[226:229], v[102:105]
	v_mfma_f32_16x16x32_bf16 v[98:101], v[138:141], v[226:229], v[98:101]
	v_mfma_f32_16x16x32_bf16 v[126:129], v[134:137], v[190:193], v[126:129]
	v_mfma_f32_16x16x32_bf16 v[122:125], v[142:145], v[190:193], v[122:125]
	v_mfma_f32_16x16x32_bf16 v[118:121], v[134:137], v[214:217], v[118:121]
	v_mfma_f32_16x16x32_bf16 v[114:117], v[142:145], v[214:217], v[114:117]
	v_mfma_f32_16x16x32_bf16 v[110:113], v[134:137], v[222:225], v[110:113]
	v_mfma_f32_16x16x32_bf16 v[106:109], v[142:145], v[222:225], v[106:109]
	v_mfma_f32_16x16x32_bf16 v[102:105], v[134:137], v[230:233], v[102:105]
	v_mfma_f32_16x16x32_bf16 v[98:101], v[142:145], v[230:233], v[98:101]
	s_setprio 0
	s_setprio 1
	v_mfma_f32_16x16x32_bf16 v[70:73], v[158:161], v[186:189], v[70:73]
	v_mfma_f32_16x16x32_bf16 v[58:61], v[166:169], v[186:189], v[58:61]
	v_mfma_f32_16x16x32_bf16 v[54:57], v[158:161], v[194:197], v[54:57]
	v_mfma_f32_16x16x32_bf16 v[50:53], v[166:169], v[194:197], v[50:53]
	v_mfma_f32_16x16x32_bf16 v[46:49], v[158:161], v[218:221], v[46:49]
	v_mfma_f32_16x16x32_bf16 v[42:45], v[166:169], v[218:221], v[42:45]
	v_mfma_f32_16x16x32_bf16 v[38:41], v[158:161], v[226:229], v[38:41]
	v_mfma_f32_16x16x32_bf16 v[34:37], v[166:169], v[226:229], v[34:37]
	v_mfma_f32_16x16x32_bf16 v[70:73], v[162:165], v[190:193], v[70:73]
	v_mfma_f32_16x16x32_bf16 v[58:61], v[180:183], v[190:193], v[58:61]
	v_mfma_f32_16x16x32_bf16 v[54:57], v[162:165], v[214:217], v[54:57]
	v_mfma_f32_16x16x32_bf16 v[50:53], v[180:183], v[214:217], v[50:53]
	v_mfma_f32_16x16x32_bf16 v[46:49], v[162:165], v[222:225], v[46:49]
	v_mfma_f32_16x16x32_bf16 v[42:45], v[180:183], v[222:225], v[42:45]
	v_mfma_f32_16x16x32_bf16 v[38:41], v[162:165], v[230:233], v[38:41]
	v_mfma_f32_16x16x32_bf16 v[34:37], v[180:183], v[230:233], v[34:37]
	s_setprio 0
	s_barrier
	s_add_i32 s60, s33, s62
	v_lshl_add_u64 v[172:173], v[172:173], 0, s[26:27]
	s_mov_b32 m0, s60
	ds_read_b128 v[186:189], v200 offset:49152
	ds_read_b128 v[190:193], v200 offset:50176
	ds_read_b128 v[194:197], v200 offset:51200
	ds_read_b128 v[214:217], v200 offset:52224
	ds_read_b128 v[218:221], v200 offset:53248
	ds_read_b128 v[222:225], v200 offset:54272
	ds_read_b128 v[226:229], v200 offset:55296
	ds_read_b128 v[230:233], v200 offset:56320
	global_load_lds_dwordx4 v[172:173], off
	s_add_i32 m0, s60, 0x2000
	s_add_u32 s58, s58, 0x80080
	v_lshl_add_u64 v[172:173], v[176:177], 0, s[26:27]
	s_addc_u32 s59, s59, 0
	s_add_i32 s60, s48, s62
	global_load_lds_dwordx4 v[172:173], off
	v_lshl_add_u64 v[172:173], s[58:59], 0, v[150:151]
	s_mov_b32 m0, s60
	s_nop 0
	global_load_lds_dwordx4 v[172:173], off
	v_lshl_add_u64 v[172:173], s[58:59], 0, v[146:147]
	s_add_i32 m0, s60, 0x2000
	s_nop 0
	global_load_lds_dwordx4 v[172:173], off
	s_waitcnt vmcnt(6)
	s_waitcnt lgkmcnt(0)
	s_barrier
	s_setprio 1
	s_waitcnt lgkmcnt(0)
	v_mfma_f32_16x16x32_bf16 v[94:97], v[130:133], v[186:189], v[94:97]
	v_mfma_f32_16x16x32_bf16 v[90:93], v[138:141], v[186:189], v[90:93]
	v_mfma_f32_16x16x32_bf16 v[86:89], v[130:133], v[194:197], v[86:89]
	v_mfma_f32_16x16x32_bf16 v[82:85], v[138:141], v[194:197], v[82:85]
	v_mfma_f32_16x16x32_bf16 v[78:81], v[130:133], v[218:221], v[78:81]
	v_mfma_f32_16x16x32_bf16 v[74:77], v[138:141], v[218:221], v[74:77]
	v_mfma_f32_16x16x32_bf16 v[66:69], v[130:133], v[226:229], v[66:69]
	v_mfma_f32_16x16x32_bf16 v[62:65], v[138:141], v[226:229], v[62:65]
	v_mfma_f32_16x16x32_bf16 v[94:97], v[134:137], v[190:193], v[94:97]
	v_mfma_f32_16x16x32_bf16 v[90:93], v[142:145], v[190:193], v[90:93]
	v_mfma_f32_16x16x32_bf16 v[86:89], v[134:137], v[214:217], v[86:89]
	v_mfma_f32_16x16x32_bf16 v[82:85], v[142:145], v[214:217], v[82:85]
	v_mfma_f32_16x16x32_bf16 v[78:81], v[134:137], v[222:225], v[78:81]
	v_mfma_f32_16x16x32_bf16 v[74:77], v[142:145], v[222:225], v[74:77]
	v_mfma_f32_16x16x32_bf16 v[66:69], v[134:137], v[230:233], v[66:69]
	v_mfma_f32_16x16x32_bf16 v[62:65], v[142:145], v[230:233], v[62:65]
	s_setprio 0
	s_setprio 1
	v_mfma_f32_16x16x32_bf16 v[30:33], v[158:161], v[186:189], v[30:33]
	v_mfma_f32_16x16x32_bf16 v[26:29], v[166:169], v[186:189], v[26:29]
	v_mfma_f32_16x16x32_bf16 v[22:25], v[158:161], v[194:197], v[22:25]
	v_mfma_f32_16x16x32_bf16 v[18:21], v[166:169], v[194:197], v[18:21]
	v_mfma_f32_16x16x32_bf16 v[14:17], v[158:161], v[218:221], v[14:17]
	v_mfma_f32_16x16x32_bf16 v[10:13], v[166:169], v[218:221], v[10:13]
	v_mfma_f32_16x16x32_bf16 v[6:9], v[158:161], v[226:229], v[6:9]
	v_mfma_f32_16x16x32_bf16 v[2:5], v[166:169], v[226:229], v[2:5]
	v_mfma_f32_16x16x32_bf16 v[30:33], v[162:165], v[190:193], v[30:33]
	v_mfma_f32_16x16x32_bf16 v[26:29], v[180:183], v[190:193], v[26:29]
	v_mfma_f32_16x16x32_bf16 v[22:25], v[162:165], v[214:217], v[22:25]
	v_mfma_f32_16x16x32_bf16 v[18:21], v[180:183], v[214:217], v[18:21]
	v_mfma_f32_16x16x32_bf16 v[14:17], v[162:165], v[222:225], v[14:17]
	v_mfma_f32_16x16x32_bf16 v[10:13], v[180:183], v[222:225], v[10:13]
	v_mfma_f32_16x16x32_bf16 v[6:9], v[162:165], v[230:233], v[6:9]
	v_mfma_f32_16x16x32_bf16 v[2:5], v[180:183], v[230:233], v[2:5]
	s_setprio 0
	s_barrier
	s_add_i32 s73, s73, 2
	s_add_u32 s71, s71, 0x100
	s_addc_u32 s72, s72, 0
	s_add_u32 s46, s46, 0x100
	s_addc_u32 s47, s47, 0
	s_cmp_gt_u32 s73, 29
	s_cbranch_scc0 .LBB0_2869
	s_and_b64 vcc, exec, s[28:29]
	s_cbranch_vccz .LBB0_2872
	s_barrier

.LBB0_2912:
	s_add_u32 s100, s46, 0xffe00000
	s_addc_u32 s101, s47, -1
	v_lshl_add_u64 v[222:223], s[100:101], 0, v[130:131]
	v_lshl_add_u64 v[224:225], s[100:101], 0, v[134:135]
	ds_read_b128 v[144:147], v160
	ds_read_b128 v[148:151], v160 offset:1024
	ds_read_b128 v[164:167], v160 offset:2048
	ds_read_b128 v[168:171], v160 offset:3072
	ds_read_b128 v[172:175], v161
	ds_read_b128 v[176:179], v161 offset:1024
	ds_read_b128 v[180:183], v161 offset:2048
	ds_read_b128 v[184:187], v161 offset:3072
	s_add_u32 s58, s46, 0xffe00080
	s_addc_u32 s59, s47, -1
	s_cmpk_eq_i32 s71, 0x7c
	s_cselect_b32 s61, s37, s59
	s_cselect_b32 s60, s43, s58
	s_cselect_b32 s59, s35, s70
	s_cselect_b32 s58, s68, s69
	v_lshl_add_u64 v[152:153], s[46:47], 0, v[142:143]
	ds_read_b128 v[188:191], v162
	ds_read_b128 v[192:195], v162 offset:1024
	ds_read_b128 v[196:199], v162 offset:2048
	ds_read_b128 v[200:203], v162 offset:3072
	ds_read_b128 v[204:207], v162 offset:4096
	ds_read_b128 v[208:211], v162 offset:5120
	ds_read_b128 v[212:215], v162 offset:6144
	ds_read_b128 v[216:219], v162 offset:7168
	s_mov_b32 m0, s64
	s_nop 0
	global_load_lds_dwordx4 v[222:223], off
	s_mov_b32 m0, s65
	s_nop 0
	global_load_lds_dwordx4 v[224:225], off
	s_add_i32 m0, s45, 0xc000
	s_nop 0
	global_load_lds_dwordx4 v[152:153], off
	v_lshl_add_u64 v[152:153], s[46:47], 0, v[140:141]
	s_add_i32 m0, s45, 0xe000
	s_nop 0
	global_load_lds_dwordx4 v[152:153], off
	s_waitcnt vmcnt(8)
	s_waitcnt lgkmcnt(0)
	s_barrier
	s_setprio 1
	s_waitcnt lgkmcnt(0)
	v_mfma_f32_16x16x32_bf16 v[126:129], v[144:147], v[188:191], v[126:129]
	v_mfma_f32_16x16x32_bf16 v[122:125], v[164:167], v[188:191], v[122:125]
	v_mfma_f32_16x16x32_bf16 v[110:113], v[144:147], v[196:199], v[110:113]
	v_mfma_f32_16x16x32_bf16 v[106:109], v[164:167], v[196:199], v[106:109]
	v_mfma_f32_16x16x32_bf16 v[94:97], v[144:147], v[204:207], v[94:97]
	v_mfma_f32_16x16x32_bf16 v[90:93], v[164:167], v[204:207], v[90:93]
	v_mfma_f32_16x16x32_bf16 v[78:81], v[144:147], v[212:215], v[78:81]
	v_mfma_f32_16x16x32_bf16 v[74:77], v[164:167], v[212:215], v[74:77]
	v_mfma_f32_16x16x32_bf16 v[126:129], v[148:151], v[192:195], v[126:129]
	v_mfma_f32_16x16x32_bf16 v[122:125], v[168:171], v[192:195], v[122:125]
	v_mfma_f32_16x16x32_bf16 v[110:113], v[148:151], v[200:203], v[110:113]
	v_mfma_f32_16x16x32_bf16 v[106:109], v[168:171], v[200:203], v[106:109]
	v_mfma_f32_16x16x32_bf16 v[94:97], v[148:151], v[208:211], v[94:97]
	v_mfma_f32_16x16x32_bf16 v[90:93], v[168:171], v[208:211], v[90:93]
	v_mfma_f32_16x16x32_bf16 v[78:81], v[148:151], v[216:219], v[78:81]
	v_mfma_f32_16x16x32_bf16 v[74:77], v[168:171], v[216:219], v[74:77]
	s_setprio 0
	s_setprio 1
	v_mfma_f32_16x16x32_bf16 v[118:121], v[172:175], v[188:191], v[118:121]
	v_mfma_f32_16x16x32_bf16 v[114:117], v[180:183], v[188:191], v[114:117]
	v_mfma_f32_16x16x32_bf16 v[102:105], v[172:175], v[196:199], v[102:105]
	v_mfma_f32_16x16x32_bf16 v[98:101], v[180:183], v[196:199], v[98:101]
	v_mfma_f32_16x16x32_bf16 v[86:89], v[172:175], v[204:207], v[86:89]
	v_mfma_f32_16x16x32_bf16 v[82:85], v[180:183], v[204:207], v[82:85]
	v_mfma_f32_16x16x32_bf16 v[70:73], v[172:175], v[212:215], v[70:73]
	v_mfma_f32_16x16x32_bf16 v[66:69], v[180:183], v[212:215], v[66:69]
	v_mfma_f32_16x16x32_bf16 v[118:121], v[176:179], v[192:195], v[118:121]
	v_mfma_f32_16x16x32_bf16 v[114:117], v[184:187], v[192:195], v[114:117]
	v_mfma_f32_16x16x32_bf16 v[102:105], v[176:179], v[200:203], v[102:105]
	v_mfma_f32_16x16x32_bf16 v[98:101], v[184:187], v[200:203], v[98:101]
	v_mfma_f32_16x16x32_bf16 v[86:89], v[176:179], v[208:211], v[86:89]
	v_mfma_f32_16x16x32_bf16 v[82:85], v[184:187], v[208:211], v[82:85]
	v_mfma_f32_16x16x32_bf16 v[70:73], v[176:179], v[216:219], v[70:73]
	v_mfma_f32_16x16x32_bf16 v[66:69], v[184:187], v[216:219], v[66:69]
	s_setprio 0
	s_barrier
	s_add_i32 s72, s0, s53
	v_lshl_add_u64 v[152:153], s[58:59], 0, v[132:133]
	s_mov_b32 m0, s72
	ds_read_b128 v[188:191], v162 offset:16384
	ds_read_b128 v[192:195], v162 offset:17408
	ds_read_b128 v[196:199], v162 offset:18432
	ds_read_b128 v[200:203], v162 offset:19456
	ds_read_b128 v[204:207], v162 offset:20480
	ds_read_b128 v[208:211], v162 offset:21504
	ds_read_b128 v[212:215], v162 offset:22528
	ds_read_b128 v[216:219], v162 offset:23552
	global_load_lds_dwordx4 v[152:153], off
	s_add_i32 m0, s72, 0x2000
	s_add_u32 s72, s58, 0x200000
	v_lshl_add_u64 v[220:221], s[58:59], 0, v[136:137]
	s_addc_u32 s73, s59, 0
	s_add_i32 s74, s1, s53
	global_load_lds_dwordx4 v[220:221], off
	v_lshl_add_u64 v[222:223], s[72:73], 0, v[132:133]
	s_mov_b32 m0, s74
	v_lshl_add_u64 v[224:225], s[60:61], 0, v[134:135]
	global_load_lds_dwordx4 v[222:223], off
	v_lshl_add_u64 v[222:223], s[72:73], 0, v[136:137]
	s_add_i32 m0, s74, 0x2000
	s_nop 0
	global_load_lds_dwordx4 v[222:223], off
	v_lshl_add_u64 v[222:223], s[60:61], 0, v[130:131]
	s_waitcnt vmcnt(6)
	s_waitcnt lgkmcnt(0)
	s_barrier
	s_setprio 1
	s_waitcnt lgkmcnt(0)
	v_mfma_f32_16x16x32_bf16 v[62:65], v[144:147], v[188:191], v[62:65]
	v_mfma_f32_16x16x32_bf16 v[58:61], v[164:167], v[188:191], v[58:61]
	v_mfma_f32_16x16x32_bf16 v[46:49], v[144:147], v[196:199], v[46:49]
	v_mfma_f32_16x16x32_bf16 v[42:45], v[164:167], v[196:199], v[42:45]
	v_mfma_f32_16x16x32_bf16 v[30:33], v[144:147], v[204:207], v[30:33]
	v_mfma_f32_16x16x32_bf16 v[26:29], v[164:167], v[204:207], v[26:29]
	v_mfma_f32_16x16x32_bf16 v[14:17], v[144:147], v[212:215], v[14:17]
	v_mfma_f32_16x16x32_bf16 v[10:13], v[164:167], v[212:215], v[10:13]
	v_mfma_f32_16x16x32_bf16 v[62:65], v[148:151], v[192:195], v[62:65]
	v_mfma_f32_16x16x32_bf16 v[58:61], v[168:171], v[192:195], v[58:61]
	v_mfma_f32_16x16x32_bf16 v[46:49], v[148:151], v[200:203], v[46:49]
	v_mfma_f32_16x16x32_bf16 v[42:45], v[168:171], v[200:203], v[42:45]
	v_mfma_f32_16x16x32_bf16 v[30:33], v[148:151], v[208:211], v[30:33]
	v_mfma_f32_16x16x32_bf16 v[26:29], v[168:171], v[208:211], v[26:29]
	v_mfma_f32_16x16x32_bf16 v[14:17], v[148:151], v[216:219], v[14:17]
	v_mfma_f32_16x16x32_bf16 v[10:13], v[168:171], v[216:219], v[10:13]
	s_setprio 0
	s_setprio 1
	v_mfma_f32_16x16x32_bf16 v[54:57], v[172:175], v[188:191], v[54:57]
	v_mfma_f32_16x16x32_bf16 v[50:53], v[180:183], v[188:191], v[50:53]
	v_mfma_f32_16x16x32_bf16 v[38:41], v[172:175], v[196:199], v[38:41]
	v_mfma_f32_16x16x32_bf16 v[34:37], v[180:183], v[196:199], v[34:37]
	v_mfma_f32_16x16x32_bf16 v[22:25], v[172:175], v[204:207], v[22:25]
	v_mfma_f32_16x16x32_bf16 v[18:21], v[180:183], v[204:207], v[18:21]
	v_mfma_f32_16x16x32_bf16 v[6:9], v[172:175], v[212:215], v[6:9]
	v_mfma_f32_16x16x32_bf16 v[2:5], v[180:183], v[212:215], v[2:5]
	v_mfma_f32_16x16x32_bf16 v[54:57], v[176:179], v[192:195], v[54:57]
	v_mfma_f32_16x16x32_bf16 v[50:53], v[184:187], v[192:195], v[50:53]
	v_mfma_f32_16x16x32_bf16 v[38:41], v[176:179], v[200:203], v[38:41]
	v_mfma_f32_16x16x32_bf16 v[34:37], v[184:187], v[200:203], v[34:37]
	v_mfma_f32_16x16x32_bf16 v[22:25], v[176:179], v[208:211], v[22:25]
	v_mfma_f32_16x16x32_bf16 v[18:21], v[184:187], v[208:211], v[18:21]
	v_mfma_f32_16x16x32_bf16 v[6:9], v[176:179], v[216:219], v[6:9]
	v_mfma_f32_16x16x32_bf16 v[2:5], v[184:187], v[216:219], v[2:5]
	s_setprio 0
	s_barrier
	v_add_u32_e32 v168, s33, v155
	v_add_u32_e32 v184, s48, v155
	ds_read_b128 v[144:147], v168
	ds_read_b128 v[148:151], v168 offset:1024
	ds_read_b128 v[164:167], v168 offset:2048
	ds_read_b128 v[168:171], v168 offset:3072
	ds_read_b128 v[172:175], v184
	ds_read_b128 v[176:179], v184 offset:1024
	ds_read_b128 v[180:183], v184 offset:2048
	ds_read_b128 v[184:187], v184 offset:3072
	s_add_u32 s60, s60, 0x200000
	s_addc_u32 s61, s61, 0
	v_lshl_add_u64 v[226:227], s[60:61], 0, v[130:131]
	ds_read_b128 v[188:191], v162 offset:32768
	ds_read_b128 v[192:195], v162 offset:33792
	ds_read_b128 v[196:199], v162 offset:34816
	ds_read_b128 v[200:203], v162 offset:35840
	ds_read_b128 v[204:207], v162 offset:36864
	ds_read_b128 v[208:211], v162 offset:37888
	ds_read_b128 v[212:215], v162 offset:38912
	ds_read_b128 v[216:219], v162 offset:39936
	s_mov_b32 m0, s45
	s_nop 0
	global_load_lds_dwordx4 v[222:223], off
	s_mov_b32 m0, s56
	s_nop 0
	global_load_lds_dwordx4 v[224:225], off
	s_mov_b32 m0, s57
	s_nop 0
	global_load_lds_dwordx4 v[226:227], off
	v_lshl_add_u64 v[226:227], s[60:61], 0, v[134:135]
	s_mov_b32 m0, s62
	s_nop 0
	global_load_lds_dwordx4 v[226:227], off
	s_waitcnt vmcnt(8)
	s_waitcnt lgkmcnt(0)
	s_barrier
	s_setprio 1
	s_waitcnt lgkmcnt(0)
	v_mfma_f32_16x16x32_bf16 v[126:129], v[144:147], v[188:191], v[126:129]
	v_mfma_f32_16x16x32_bf16 v[122:125], v[164:167], v[188:191], v[122:125]
	v_mfma_f32_16x16x32_bf16 v[110:113], v[144:147], v[196:199], v[110:113]
	v_mfma_f32_16x16x32_bf16 v[106:109], v[164:167], v[196:199], v[106:109]
	v_mfma_f32_16x16x32_bf16 v[94:97], v[144:147], v[204:207], v[94:97]
	v_mfma_f32_16x16x32_bf16 v[90:93], v[164:167], v[204:207], v[90:93]
	v_mfma_f32_16x16x32_bf16 v[78:81], v[144:147], v[212:215], v[78:81]
	v_mfma_f32_16x16x32_bf16 v[74:77], v[164:167], v[212:215], v[74:77]
	v_mfma_f32_16x16x32_bf16 v[126:129], v[148:151], v[192:195], v[126:129]
	v_mfma_f32_16x16x32_bf16 v[122:125], v[168:171], v[192:195], v[122:125]
	v_mfma_f32_16x16x32_bf16 v[110:113], v[148:151], v[200:203], v[110:113]
	v_mfma_f32_16x16x32_bf16 v[106:109], v[168:171], v[200:203], v[106:109]
	v_mfma_f32_16x16x32_bf16 v[94:97], v[148:151], v[208:211], v[94:97]
	v_mfma_f32_16x16x32_bf16 v[90:93], v[168:171], v[208:211], v[90:93]
	v_mfma_f32_16x16x32_bf16 v[78:81], v[148:151], v[216:219], v[78:81]
	v_mfma_f32_16x16x32_bf16 v[74:77], v[168:171], v[216:219], v[74:77]
	s_setprio 0
	s_setprio 1
	v_mfma_f32_16x16x32_bf16 v[118:121], v[172:175], v[188:191], v[118:121]
	v_mfma_f32_16x16x32_bf16 v[114:117], v[180:183], v[188:191], v[114:117]
	v_mfma_f32_16x16x32_bf16 v[102:105], v[172:175], v[196:199], v[102:105]
	v_mfma_f32_16x16x32_bf16 v[98:101], v[180:183], v[196:199], v[98:101]
	v_mfma_f32_16x16x32_bf16 v[86:89], v[172:175], v[204:207], v[86:89]
	v_mfma_f32_16x16x32_bf16 v[82:85], v[180:183], v[204:207], v[82:85]
	v_mfma_f32_16x16x32_bf16 v[70:73], v[172:175], v[212:215], v[70:73]
	v_mfma_f32_16x16x32_bf16 v[66:69], v[180:183], v[212:215], v[66:69]
	v_mfma_f32_16x16x32_bf16 v[118:121], v[176:179], v[192:195], v[118:121]
	v_mfma_f32_16x16x32_bf16 v[114:117], v[184:187], v[192:195], v[114:117]
	v_mfma_f32_16x16x32_bf16 v[102:105], v[176:179], v[200:203], v[102:105]
	v_mfma_f32_16x16x32_bf16 v[98:101], v[184:187], v[200:203], v[98:101]
	v_mfma_f32_16x16x32_bf16 v[86:89], v[176:179], v[208:211], v[86:89]
	v_mfma_f32_16x16x32_bf16 v[82:85], v[184:187], v[208:211], v[82:85]
	v_mfma_f32_16x16x32_bf16 v[70:73], v[176:179], v[216:219], v[70:73]
	v_mfma_f32_16x16x32_bf16 v[66:69], v[184:187], v[216:219], v[66:69]
	s_setprio 0
	s_barrier
	s_add_i32 s60, s33, s53
	v_lshl_add_u64 v[152:153], v[152:153], 0, s[26:27]
	s_mov_b32 m0, s60
	ds_read_b128 v[188:191], v162 offset:49152
	ds_read_b128 v[192:195], v162 offset:50176
	ds_read_b128 v[196:199], v162 offset:51200
	ds_read_b128 v[200:203], v162 offset:52224
	ds_read_b128 v[204:207], v162 offset:53248
	ds_read_b128 v[208:211], v162 offset:54272
	ds_read_b128 v[212:215], v162 offset:55296
	ds_read_b128 v[216:219], v162 offset:56320
	global_load_lds_dwordx4 v[152:153], off
	s_add_i32 m0, s60, 0x2000
	s_add_u32 s58, s58, 0x200080
	v_lshl_add_u64 v[152:153], v[220:221], 0, s[26:27]
	s_addc_u32 s59, s59, 0
	s_add_i32 s60, s48, s53
	global_load_lds_dwordx4 v[152:153], off
	v_lshl_add_u64 v[152:153], s[58:59], 0, v[132:133]
	s_mov_b32 m0, s60
	s_nop 0
	global_load_lds_dwordx4 v[152:153], off
	v_lshl_add_u64 v[152:153], s[58:59], 0, v[136:137]
	s_add_i32 m0, s60, 0x2000
	s_nop 0
	global_load_lds_dwordx4 v[152:153], off
	s_waitcnt vmcnt(6)
	s_waitcnt lgkmcnt(0)
	s_barrier
	s_setprio 1
	s_waitcnt lgkmcnt(0)
	v_mfma_f32_16x16x32_bf16 v[62:65], v[144:147], v[188:191], v[62:65]
	v_mfma_f32_16x16x32_bf16 v[58:61], v[164:167], v[188:191], v[58:61]
	v_mfma_f32_16x16x32_bf16 v[46:49], v[144:147], v[196:199], v[46:49]
	v_mfma_f32_16x16x32_bf16 v[42:45], v[164:167], v[196:199], v[42:45]
	v_mfma_f32_16x16x32_bf16 v[30:33], v[144:147], v[204:207], v[30:33]
	v_mfma_f32_16x16x32_bf16 v[26:29], v[164:167], v[204:207], v[26:29]
	v_mfma_f32_16x16x32_bf16 v[14:17], v[144:147], v[212:215], v[14:17]
	v_mfma_f32_16x16x32_bf16 v[10:13], v[164:167], v[212:215], v[10:13]
	v_mfma_f32_16x16x32_bf16 v[62:65], v[148:151], v[192:195], v[62:65]
	v_mfma_f32_16x16x32_bf16 v[58:61], v[168:171], v[192:195], v[58:61]
	v_mfma_f32_16x16x32_bf16 v[46:49], v[148:151], v[200:203], v[46:49]
	v_mfma_f32_16x16x32_bf16 v[42:45], v[168:171], v[200:203], v[42:45]
	v_mfma_f32_16x16x32_bf16 v[30:33], v[148:151], v[208:211], v[30:33]
	v_mfma_f32_16x16x32_bf16 v[26:29], v[168:171], v[208:211], v[26:29]
	v_mfma_f32_16x16x32_bf16 v[14:17], v[148:151], v[216:219], v[14:17]
	v_mfma_f32_16x16x32_bf16 v[10:13], v[168:171], v[216:219], v[10:13]
	s_setprio 0
	s_setprio 1
	v_mfma_f32_16x16x32_bf16 v[54:57], v[172:175], v[188:191], v[54:57]
	v_mfma_f32_16x16x32_bf16 v[50:53], v[180:183], v[188:191], v[50:53]
	v_mfma_f32_16x16x32_bf16 v[38:41], v[172:175], v[196:199], v[38:41]
	v_mfma_f32_16x16x32_bf16 v[34:37], v[180:183], v[196:199], v[34:37]
	v_mfma_f32_16x16x32_bf16 v[22:25], v[172:175], v[204:207], v[22:25]
	v_mfma_f32_16x16x32_bf16 v[18:21], v[180:183], v[204:207], v[18:21]
	v_mfma_f32_16x16x32_bf16 v[6:9], v[172:175], v[212:215], v[6:9]
	v_mfma_f32_16x16x32_bf16 v[2:5], v[180:183], v[212:215], v[2:5]
	v_mfma_f32_16x16x32_bf16 v[54:57], v[176:179], v[192:195], v[54:57]
	v_mfma_f32_16x16x32_bf16 v[50:53], v[184:187], v[192:195], v[50:53]
	v_mfma_f32_16x16x32_bf16 v[38:41], v[176:179], v[200:203], v[38:41]
	v_mfma_f32_16x16x32_bf16 v[34:37], v[184:187], v[200:203], v[34:37]
	v_mfma_f32_16x16x32_bf16 v[22:25], v[176:179], v[208:211], v[22:25]
	v_mfma_f32_16x16x32_bf16 v[18:21], v[184:187], v[208:211], v[18:21]
	v_mfma_f32_16x16x32_bf16 v[6:9], v[176:179], v[216:219], v[6:9]
	v_mfma_f32_16x16x32_bf16 v[2:5], v[184:187], v[216:219], v[2:5]
	s_setprio 0
	s_barrier
	s_add_i32 s71, s71, 2
	s_add_u32 s69, s69, 0x100
	s_addc_u32 s70, s70, 0
	s_add_u32 s46, s46, 0x100
	s_addc_u32 s47, s47, 0
	s_cmpk_gt_u32 s71, 0x7d
	s_cbranch_scc0 .LBB0_2912
	s_and_b64 vcc, exec, s[28:29]
	s_cbranch_vccz .LBB0_2915
	s_barrier

.LBB0_3004:
	s_add_u32 s100, s62, 0xfff80000
	s_addc_u32 s101, s63, -1
	v_lshl_add_u64 v[228:229], s[100:101], 0, v[130:131]
	v_lshl_add_u64 v[230:231], s[100:101], 0, v[134:135]
	ds_read_b128 v[150:153], v173
	ds_read_b128 v[154:157], v173 offset:1024
	ds_read_b128 v[158:161], v173 offset:2048
	ds_read_b128 v[162:165], v173 offset:3072
	ds_read_b128 v[178:181], v174
	ds_read_b128 v[182:185], v174 offset:1024
	ds_read_b128 v[186:189], v174 offset:2048
	ds_read_b128 v[190:193], v174 offset:3072
	s_add_u32 s64, s62, 0xfff80080
	s_addc_u32 s65, s63, -1
	s_cmp_eq_u32 s71, 28
	s_cselect_b32 s67, s43, s65
	s_cselect_b32 s66, s59, s64
	s_cselect_b32 s65, s41, s70
	s_cselect_b32 s64, s68, s69
	v_lshl_add_u64 v[168:169], s[62:63], 0, v[142:143]
	ds_read_b128 v[194:197], v175
	ds_read_b128 v[198:201], v175 offset:1024
	ds_read_b128 v[202:205], v175 offset:2048
	ds_read_b128 v[206:209], v175 offset:3072
	ds_read_b128 v[210:213], v175 offset:4096
	ds_read_b128 v[214:217], v175 offset:5120
	ds_read_b128 v[218:221], v175 offset:6144
	ds_read_b128 v[222:225], v175 offset:7168
	s_mov_b32 m0, s51
	s_nop 0
	global_load_lds_dwordx4 v[228:229], off
	s_mov_b32 m0, s52
	s_nop 0
	global_load_lds_dwordx4 v[230:231], off
	s_add_i32 m0, s1, 0xc000
	s_nop 0
	global_load_lds_dwordx4 v[168:169], off
	v_lshl_add_u64 v[168:169], s[62:63], 0, v[140:141]
	s_add_i32 m0, s1, 0xe000
	s_nop 0
	global_load_lds_dwordx4 v[168:169], off
	s_waitcnt vmcnt(8)
	s_waitcnt lgkmcnt(0)
	s_barrier
	s_setprio 1
	s_waitcnt lgkmcnt(0)
	v_mfma_f32_16x16x32_bf16 v[126:129], v[150:153], v[194:197], v[126:129]
	v_mfma_f32_16x16x32_bf16 v[122:125], v[158:161], v[194:197], v[122:125]
	v_mfma_f32_16x16x32_bf16 v[110:113], v[150:153], v[202:205], v[110:113]
	v_mfma_f32_16x16x32_bf16 v[106:109], v[158:161], v[202:205], v[106:109]
	v_mfma_f32_16x16x32_bf16 v[94:97], v[150:153], v[210:213], v[94:97]
	v_mfma_f32_16x16x32_bf16 v[90:93], v[158:161], v[210:213], v[90:93]
	v_mfma_f32_16x16x32_bf16 v[78:81], v[150:153], v[218:221], v[78:81]
	v_mfma_f32_16x16x32_bf16 v[74:77], v[158:161], v[218:221], v[74:77]
	v_mfma_f32_16x16x32_bf16 v[126:129], v[154:157], v[198:201], v[126:129]
	v_mfma_f32_16x16x32_bf16 v[122:125], v[162:165], v[198:201], v[122:125]
	v_mfma_f32_16x16x32_bf16 v[110:113], v[154:157], v[206:209], v[110:113]
	v_mfma_f32_16x16x32_bf16 v[106:109], v[162:165], v[206:209], v[106:109]
	v_mfma_f32_16x16x32_bf16 v[94:97], v[154:157], v[214:217], v[94:97]
	v_mfma_f32_16x16x32_bf16 v[90:93], v[162:165], v[214:217], v[90:93]
	v_mfma_f32_16x16x32_bf16 v[78:81], v[154:157], v[222:225], v[78:81]
	v_mfma_f32_16x16x32_bf16 v[74:77], v[162:165], v[222:225], v[74:77]
	s_setprio 0
	s_setprio 1
	v_mfma_f32_16x16x32_bf16 v[118:121], v[178:181], v[194:197], v[118:121]
	v_mfma_f32_16x16x32_bf16 v[114:117], v[186:189], v[194:197], v[114:117]
	v_mfma_f32_16x16x32_bf16 v[102:105], v[178:181], v[202:205], v[102:105]
	v_mfma_f32_16x16x32_bf16 v[98:101], v[186:189], v[202:205], v[98:101]
	v_mfma_f32_16x16x32_bf16 v[86:89], v[178:181], v[210:213], v[86:89]
	v_mfma_f32_16x16x32_bf16 v[82:85], v[186:189], v[210:213], v[82:85]
	v_mfma_f32_16x16x32_bf16 v[70:73], v[178:181], v[218:221], v[70:73]
	v_mfma_f32_16x16x32_bf16 v[66:69], v[186:189], v[218:221], v[66:69]
	v_mfma_f32_16x16x32_bf16 v[118:121], v[182:185], v[198:201], v[118:121]
	v_mfma_f32_16x16x32_bf16 v[114:117], v[190:193], v[198:201], v[114:117]
	v_mfma_f32_16x16x32_bf16 v[102:105], v[182:185], v[206:209], v[102:105]
	v_mfma_f32_16x16x32_bf16 v[98:101], v[190:193], v[206:209], v[98:101]
	v_mfma_f32_16x16x32_bf16 v[86:89], v[182:185], v[214:217], v[86:89]
	v_mfma_f32_16x16x32_bf16 v[82:85], v[190:193], v[214:217], v[82:85]
	v_mfma_f32_16x16x32_bf16 v[70:73], v[182:185], v[222:225], v[70:73]
	v_mfma_f32_16x16x32_bf16 v[66:69], v[190:193], v[222:225], v[66:69]
	s_setprio 0
	s_barrier
	s_add_i32 s72, s57, s0
	v_lshl_add_u64 v[168:169], s[64:65], 0, v[132:133]
	s_mov_b32 m0, s72
	ds_read_b128 v[194:197], v175 offset:16384
	ds_read_b128 v[198:201], v175 offset:17408
	ds_read_b128 v[202:205], v175 offset:18432
	ds_read_b128 v[206:209], v175 offset:19456
	ds_read_b128 v[210:213], v175 offset:20480
	ds_read_b128 v[214:217], v175 offset:21504
	ds_read_b128 v[218:221], v175 offset:22528
	ds_read_b128 v[222:225], v175 offset:23552
	global_load_lds_dwordx4 v[168:169], off
	s_add_i32 m0, s72, 0x2000
	s_add_u32 s72, s64, 0x80000
	v_lshl_add_u64 v[226:227], s[64:65], 0, v[136:137]
	s_addc_u32 s73, s65, 0
	s_add_i32 s74, s61, s0
	global_load_lds_dwordx4 v[226:227], off
	v_lshl_add_u64 v[228:229], s[72:73], 0, v[132:133]
	s_mov_b32 m0, s74
	v_lshl_add_u64 v[230:231], s[66:67], 0, v[134:135]
	global_load_lds_dwordx4 v[228:229], off
	v_lshl_add_u64 v[228:229], s[72:73], 0, v[136:137]
	s_add_i32 m0, s74, 0x2000
	s_nop 0
	global_load_lds_dwordx4 v[228:229], off
	v_lshl_add_u64 v[228:229], s[66:67], 0, v[130:131]
	s_waitcnt vmcnt(6)
	s_waitcnt lgkmcnt(0)
	s_barrier
	s_setprio 1
	s_waitcnt lgkmcnt(0)
	v_mfma_f32_16x16x32_bf16 v[62:65], v[150:153], v[194:197], v[62:65]
	v_mfma_f32_16x16x32_bf16 v[58:61], v[158:161], v[194:197], v[58:61]
	v_mfma_f32_16x16x32_bf16 v[46:49], v[150:153], v[202:205], v[46:49]
	v_mfma_f32_16x16x32_bf16 v[42:45], v[158:161], v[202:205], v[42:45]
	v_mfma_f32_16x16x32_bf16 v[30:33], v[150:153], v[210:213], v[30:33]
	v_mfma_f32_16x16x32_bf16 v[26:29], v[158:161], v[210:213], v[26:29]
	v_mfma_f32_16x16x32_bf16 v[14:17], v[150:153], v[218:221], v[14:17]
	v_mfma_f32_16x16x32_bf16 v[10:13], v[158:161], v[218:221], v[10:13]
	v_mfma_f32_16x16x32_bf16 v[62:65], v[154:157], v[198:201], v[62:65]
	v_mfma_f32_16x16x32_bf16 v[58:61], v[162:165], v[198:201], v[58:61]
	v_mfma_f32_16x16x32_bf16 v[46:49], v[154:157], v[206:209], v[46:49]
	v_mfma_f32_16x16x32_bf16 v[42:45], v[162:165], v[206:209], v[42:45]
	v_mfma_f32_16x16x32_bf16 v[30:33], v[154:157], v[214:217], v[30:33]
	v_mfma_f32_16x16x32_bf16 v[26:29], v[162:165], v[214:217], v[26:29]
	v_mfma_f32_16x16x32_bf16 v[14:17], v[154:157], v[222:225], v[14:17]
	v_mfma_f32_16x16x32_bf16 v[10:13], v[162:165], v[222:225], v[10:13]
	s_setprio 0
	s_setprio 1
	v_mfma_f32_16x16x32_bf16 v[54:57], v[178:181], v[194:197], v[54:57]
	v_mfma_f32_16x16x32_bf16 v[50:53], v[186:189], v[194:197], v[50:53]
	v_mfma_f32_16x16x32_bf16 v[38:41], v[178:181], v[202:205], v[38:41]
	v_mfma_f32_16x16x32_bf16 v[34:37], v[186:189], v[202:205], v[34:37]
	v_mfma_f32_16x16x32_bf16 v[22:25], v[178:181], v[210:213], v[22:25]
	v_mfma_f32_16x16x32_bf16 v[18:21], v[186:189], v[210:213], v[18:21]
	v_mfma_f32_16x16x32_bf16 v[6:9], v[178:181], v[218:221], v[6:9]
	v_mfma_f32_16x16x32_bf16 v[2:5], v[186:189], v[218:221], v[2:5]
	v_mfma_f32_16x16x32_bf16 v[54:57], v[182:185], v[198:201], v[54:57]
	v_mfma_f32_16x16x32_bf16 v[50:53], v[190:193], v[198:201], v[50:53]
	v_mfma_f32_16x16x32_bf16 v[38:41], v[182:185], v[206:209], v[38:41]
	v_mfma_f32_16x16x32_bf16 v[34:37], v[190:193], v[206:209], v[34:37]
	v_mfma_f32_16x16x32_bf16 v[22:25], v[182:185], v[214:217], v[22:25]
	v_mfma_f32_16x16x32_bf16 v[18:21], v[190:193], v[214:217], v[18:21]
	v_mfma_f32_16x16x32_bf16 v[6:9], v[182:185], v[222:225], v[6:9]
	v_mfma_f32_16x16x32_bf16 v[2:5], v[190:193], v[222:225], v[2:5]
	s_setprio 0
	s_barrier
	s_add_i32 s72, 0, 0x18000
	v_add_u32_e32 v149, s72, v171
	s_add_i32 s73, 0, 0x1c000
	ds_read_b128 v[150:153], v149
	ds_read_b128 v[154:157], v149 offset:1024
	ds_read_b128 v[158:161], v149 offset:2048
	ds_read_b128 v[162:165], v149 offset:3072
	v_add_u32_e32 v149, s73, v171
	ds_read_b128 v[178:181], v149
	ds_read_b128 v[182:185], v149 offset:1024
	ds_read_b128 v[186:189], v149 offset:2048
	ds_read_b128 v[190:193], v149 offset:3072
	s_add_u32 s66, s66, 0x80000
	s_addc_u32 s67, s67, 0
	v_lshl_add_u64 v[232:233], s[66:67], 0, v[130:131]
	ds_read_b128 v[194:197], v175 offset:32768
	ds_read_b128 v[198:201], v175 offset:33792
	ds_read_b128 v[202:205], v175 offset:34816
	ds_read_b128 v[206:209], v175 offset:35840
	ds_read_b128 v[210:213], v175 offset:36864
	ds_read_b128 v[214:217], v175 offset:37888
	ds_read_b128 v[218:221], v175 offset:38912
	ds_read_b128 v[222:225], v175 offset:39936
	s_mov_b32 m0, s1
	s_nop 0
	global_load_lds_dwordx4 v[228:229], off
	s_mov_b32 m0, s33
	s_nop 0
	global_load_lds_dwordx4 v[230:231], off
	s_mov_b32 m0, s39
	s_nop 0
	global_load_lds_dwordx4 v[232:233], off
	v_lshl_add_u64 v[232:233], s[66:67], 0, v[134:135]
	s_mov_b32 m0, s48
	s_nop 0
	global_load_lds_dwordx4 v[232:233], off
	s_waitcnt vmcnt(8)
	s_waitcnt lgkmcnt(0)
	s_barrier
	s_setprio 1
	s_waitcnt lgkmcnt(0)
	v_mfma_f32_16x16x32_bf16 v[126:129], v[150:153], v[194:197], v[126:129]
	v_mfma_f32_16x16x32_bf16 v[122:125], v[158:161], v[194:197], v[122:125]
	v_mfma_f32_16x16x32_bf16 v[110:113], v[150:153], v[202:205], v[110:113]
	v_mfma_f32_16x16x32_bf16 v[106:109], v[158:161], v[202:205], v[106:109]
	v_mfma_f32_16x16x32_bf16 v[94:97], v[150:153], v[210:213], v[94:97]
	v_mfma_f32_16x16x32_bf16 v[90:93], v[158:161], v[210:213], v[90:93]
	v_mfma_f32_16x16x32_bf16 v[78:81], v[150:153], v[218:221], v[78:81]
	v_mfma_f32_16x16x32_bf16 v[74:77], v[158:161], v[218:221], v[74:77]
	v_mfma_f32_16x16x32_bf16 v[126:129], v[154:157], v[198:201], v[126:129]
	v_mfma_f32_16x16x32_bf16 v[122:125], v[162:165], v[198:201], v[122:125]
	v_mfma_f32_16x16x32_bf16 v[110:113], v[154:157], v[206:209], v[110:113]
	v_mfma_f32_16x16x32_bf16 v[106:109], v[162:165], v[206:209], v[106:109]
	v_mfma_f32_16x16x32_bf16 v[94:97], v[154:157], v[214:217], v[94:97]
	v_mfma_f32_16x16x32_bf16 v[90:93], v[162:165], v[214:217], v[90:93]
	v_mfma_f32_16x16x32_bf16 v[78:81], v[154:157], v[222:225], v[78:81]
	v_mfma_f32_16x16x32_bf16 v[74:77], v[162:165], v[222:225], v[74:77]
	s_setprio 0
	s_setprio 1
	v_mfma_f32_16x16x32_bf16 v[118:121], v[178:181], v[194:197], v[118:121]
	v_mfma_f32_16x16x32_bf16 v[114:117], v[186:189], v[194:197], v[114:117]
	v_mfma_f32_16x16x32_bf16 v[102:105], v[178:181], v[202:205], v[102:105]
	v_mfma_f32_16x16x32_bf16 v[98:101], v[186:189], v[202:205], v[98:101]
	v_mfma_f32_16x16x32_bf16 v[86:89], v[178:181], v[210:213], v[86:89]
	v_mfma_f32_16x16x32_bf16 v[82:85], v[186:189], v[210:213], v[82:85]
	v_mfma_f32_16x16x32_bf16 v[70:73], v[178:181], v[218:221], v[70:73]
	v_mfma_f32_16x16x32_bf16 v[66:69], v[186:189], v[218:221], v[66:69]
	v_mfma_f32_16x16x32_bf16 v[118:121], v[182:185], v[198:201], v[118:121]
	v_mfma_f32_16x16x32_bf16 v[114:117], v[190:193], v[198:201], v[114:117]
	v_mfma_f32_16x16x32_bf16 v[102:105], v[182:185], v[206:209], v[102:105]
	v_mfma_f32_16x16x32_bf16 v[98:101], v[190:193], v[206:209], v[98:101]
	v_mfma_f32_16x16x32_bf16 v[86:89], v[182:185], v[214:217], v[86:89]
	v_mfma_f32_16x16x32_bf16 v[82:85], v[190:193], v[214:217], v[82:85]
	v_mfma_f32_16x16x32_bf16 v[70:73], v[182:185], v[222:225], v[70:73]
	v_mfma_f32_16x16x32_bf16 v[66:69], v[190:193], v[222:225], v[66:69]
	s_setprio 0
	s_barrier
	s_add_i32 s66, s72, s0
	v_lshl_add_u64 v[168:169], v[168:169], 0, s[34:35]
	s_mov_b32 m0, s66
	ds_read_b128 v[194:197], v175 offset:49152
	ds_read_b128 v[198:201], v175 offset:50176
	ds_read_b128 v[202:205], v175 offset:51200
	ds_read_b128 v[206:209], v175 offset:52224
	ds_read_b128 v[210:213], v175 offset:53248
	ds_read_b128 v[214:217], v175 offset:54272
	ds_read_b128 v[218:221], v175 offset:55296
	ds_read_b128 v[222:225], v175 offset:56320
	global_load_lds_dwordx4 v[168:169], off
	s_add_i32 m0, s66, 0x2000
	s_add_u32 s64, s64, 0x80080
	v_lshl_add_u64 v[168:169], v[226:227], 0, s[34:35]
	s_addc_u32 s65, s65, 0
	s_add_i32 s66, s73, s0
	global_load_lds_dwordx4 v[168:169], off
	v_lshl_add_u64 v[168:169], s[64:65], 0, v[132:133]
	s_mov_b32 m0, s66
	s_nop 0
	global_load_lds_dwordx4 v[168:169], off
	v_lshl_add_u64 v[168:169], s[64:65], 0, v[136:137]
	s_add_i32 m0, s66, 0x2000
	s_nop 0
	global_load_lds_dwordx4 v[168:169], off
	s_waitcnt vmcnt(6)
	s_waitcnt lgkmcnt(0)
	s_barrier
	s_setprio 1
	s_waitcnt lgkmcnt(0)
	v_mfma_f32_16x16x32_bf16 v[62:65], v[150:153], v[194:197], v[62:65]
	v_mfma_f32_16x16x32_bf16 v[58:61], v[158:161], v[194:197], v[58:61]
	v_mfma_f32_16x16x32_bf16 v[46:49], v[150:153], v[202:205], v[46:49]
	v_mfma_f32_16x16x32_bf16 v[42:45], v[158:161], v[202:205], v[42:45]
	v_mfma_f32_16x16x32_bf16 v[30:33], v[150:153], v[210:213], v[30:33]
	v_mfma_f32_16x16x32_bf16 v[26:29], v[158:161], v[210:213], v[26:29]
	v_mfma_f32_16x16x32_bf16 v[14:17], v[150:153], v[218:221], v[14:17]
	v_mfma_f32_16x16x32_bf16 v[10:13], v[158:161], v[218:221], v[10:13]
	v_mfma_f32_16x16x32_bf16 v[62:65], v[154:157], v[198:201], v[62:65]
	v_mfma_f32_16x16x32_bf16 v[58:61], v[162:165], v[198:201], v[58:61]
	v_mfma_f32_16x16x32_bf16 v[46:49], v[154:157], v[206:209], v[46:49]
	v_mfma_f32_16x16x32_bf16 v[42:45], v[162:165], v[206:209], v[42:45]
	v_mfma_f32_16x16x32_bf16 v[30:33], v[154:157], v[214:217], v[30:33]
	v_mfma_f32_16x16x32_bf16 v[26:29], v[162:165], v[214:217], v[26:29]
	v_mfma_f32_16x16x32_bf16 v[14:17], v[154:157], v[222:225], v[14:17]
	v_mfma_f32_16x16x32_bf16 v[10:13], v[162:165], v[222:225], v[10:13]
	s_setprio 0
	s_setprio 1
	v_mfma_f32_16x16x32_bf16 v[54:57], v[178:181], v[194:197], v[54:57]
	v_mfma_f32_16x16x32_bf16 v[50:53], v[186:189], v[194:197], v[50:53]
	v_mfma_f32_16x16x32_bf16 v[38:41], v[178:181], v[202:205], v[38:41]
	v_mfma_f32_16x16x32_bf16 v[34:37], v[186:189], v[202:205], v[34:37]
	v_mfma_f32_16x16x32_bf16 v[22:25], v[178:181], v[210:213], v[22:25]
	v_mfma_f32_16x16x32_bf16 v[18:21], v[186:189], v[210:213], v[18:21]
	v_mfma_f32_16x16x32_bf16 v[6:9], v[178:181], v[218:221], v[6:9]
	v_mfma_f32_16x16x32_bf16 v[2:5], v[186:189], v[218:221], v[2:5]
	v_mfma_f32_16x16x32_bf16 v[54:57], v[182:185], v[198:201], v[54:57]
	v_mfma_f32_16x16x32_bf16 v[50:53], v[190:193], v[198:201], v[50:53]
	v_mfma_f32_16x16x32_bf16 v[38:41], v[182:185], v[206:209], v[38:41]
	v_mfma_f32_16x16x32_bf16 v[34:37], v[190:193], v[206:209], v[34:37]
	v_mfma_f32_16x16x32_bf16 v[22:25], v[182:185], v[214:217], v[22:25]
	v_mfma_f32_16x16x32_bf16 v[18:21], v[190:193], v[214:217], v[18:21]
	v_mfma_f32_16x16x32_bf16 v[6:9], v[182:185], v[222:225], v[6:9]
	v_mfma_f32_16x16x32_bf16 v[2:5], v[190:193], v[222:225], v[2:5]
	s_setprio 0
	s_barrier
	s_add_i32 s71, s71, 2
	s_add_u32 s69, s69, 0x100
	s_addc_u32 s70, s70, 0
	s_add_u32 s62, s62, 0x100
	s_addc_u32 s63, s63, 0
	s_cmp_gt_u32 s71, 29
	s_cbranch_scc0 .LBB0_3004
	s_and_b64 vcc, exec, s[36:37]
	s_cbranch_vccz .LBB0_3007
	s_barrier

	.amdhsa_kernel _Z8skel_fwd4Args
		.amdhsa_group_segment_fixed_size 0
		.amdhsa_private_segment_fixed_size 0
		.amdhsa_kernarg_size 560
		.amdhsa_user_sgpr_count 2
		.amdhsa_user_sgpr_dispatch_ptr 0
		.amdhsa_user_sgpr_queue_ptr 0
		.amdhsa_user_sgpr_kernarg_segment_ptr 1
		.amdhsa_user_sgpr_dispatch_id 0
		.amdhsa_user_sgpr_kernarg_preload_length 0
		.amdhsa_user_sgpr_kernarg_preload_offset 0
		.amdhsa_user_sgpr_private_segment_size 0
		.amdhsa_uses_dynamic_stack 0
		.amdhsa_enable_private_segment 0
		.amdhsa_system_sgpr_workgroup_id_x 1
		.amdhsa_system_sgpr_workgroup_id_y 0
		.amdhsa_system_sgpr_workgroup_id_z 0
		.amdhsa_system_sgpr_workgroup_info 0
		.amdhsa_system_vgpr_workitem_id 0
		.amdhsa_next_free_vgpr 256
		.amdhsa_next_free_sgpr 102
		.amdhsa_accum_offset 256
		.amdhsa_reserve_vcc 1
		.amdhsa_float_round_mode_32 0
		.amdhsa_float_round_mode_16_64 0
		.amdhsa_float_denorm_mode_32 3
		.amdhsa_float_denorm_mode_16_64 3
		.amdhsa_dx10_clamp 1
		.amdhsa_ieee_mode 1
		.amdhsa_fp16_overflow 0
		.amdhsa_tg_split 0
		.amdhsa_exception_fp_ieee_invalid_op 0
		.amdhsa_exception_fp_denorm_src 0
		.amdhsa_exception_fp_ieee_div_zero 0
		.amdhsa_exception_fp_ieee_overflow 0
		.amdhsa_exception_fp_ieee_underflow 0
		.amdhsa_exception_fp_ieee_inexact 0
		.amdhsa_exception_int_div_zero 0
	.end_amdhsa_kernel

amdhsa.kernels:
  - .agpr_count:     0
    .args:
      - .offset:         0
        .size:           304
        .value_kind:     by_value
      - .offset:         304
        .size:           4
        .value_kind:     hidden_block_count_x
      - .offset:         308
        .size:           4
        .value_kind:     hidden_block_count_y
      - .offset:         312
        .size:           4
        .value_kind:     hidden_block_count_z
      - .offset:         316
        .size:           2
        .value_kind:     hidden_group_size_x
      - .offset:         318
        .size:           2
        .value_kind:     hidden_group_size_y
      - .offset:         320
        .size:           2
        .value_kind:     hidden_group_size_z
      - .offset:         322
        .size:           2
        .value_kind:     hidden_remainder_x
      - .offset:         324
        .size:           2
        .value_kind:     hidden_remainder_y
      - .offset:         326
        .size:           2
        .value_kind:     hidden_remainder_z
      - .offset:         344
        .size:           8
        .value_kind:     hidden_global_offset_x
      - .offset:         352
        .size:           8
        .value_kind:     hidden_global_offset_y
      - .offset:         360
        .size:           8
        .value_kind:     hidden_global_offset_z
      - .offset:         368
        .size:           2
        .value_kind:     hidden_grid_dims
      - .offset:         424
        .size:           4
        .value_kind:     hidden_dynamic_lds_size
    .group_segment_fixed_size: 0
    .kernarg_segment_align: 8
    .kernarg_segment_size: 560
    .language:       OpenCL C
    .language_version:
      - 2
      - 0
    .max_flat_workgroup_size: 512
    .name:           _Z8skel_fwd4Args
    .private_segment_fixed_size: 0
    .sgpr_count:     108
    .sgpr_spill_count: 70
    .symbol:         _Z8skel_fwd4Args.kd
    .uniform_work_group_size: 1
    .uses_dynamic_stack: false
    .vgpr_count:     256
    .vgpr_spill_count: 0
    .wavefront_size: 64
